# hot loop headers (GEMM K-loops, attention tile loops) aligned to 8 bytes with .p2align 3
# baseline (speedup 1.0000x reference)
; template <class Epi>
; DI void gemm_phase(PG8_LAS unsigned char* lds, const Gemm g, const StaticOrder& S, const Epi& E, const int wv) {
;     ...
;     const bool has_next = S.next(ui + 1, nxt);
;     const char* nA = has_next ? (const char*)g.A + (size_t)nxt.pm * tstep : cA; const char* nB = has_next ? (const char*)g.Bt + (size_t)nxt.pn * tstep : cB;
;     ...
; #pragma unroll
;     for (int a = 0; a < 2; ++a)
; #pragma unroll
;       for (int b = 0; b < 2; ++b)
; #pragma unroll
;         for (int m = 0; m < 4; ++m)
; #pragma unroll
;           for (int n = 0; n < 2; ++n) acc[a][b][m][n] = (f32x4){0.f, 0.f, 0.f, 0.f};
;     cur = nxt; cA = nA; cB = nB; ++ui;
.LBB0_88:
	s_ashr_i32 s19, s18, 31
	s_lshl_b64 s[36:37], s[18:19], 19
	s_add_u32 s38, s59, s36
	s_addc_u32 s39, s60, s37
	s_and_b64 s[36:37], exec, s[40:41]
	s_cselect_b32 s19, s7, s39
	s_cselect_b32 s44, s6, s38
	s_ashr_i32 s17, s16, 31
	s_lshl_b64 s[36:37], s[16:17], 19
	s_add_u32 s36, s14, s36
	s_addc_u32 s37, s15, s37
	s_and_b64 s[42:43], exec, s[40:41]
	s_cselect_b32 s17, s9, s37
	s_cselect_b32 s45, s8, s36
	s_add_u32 s6, s6, 0x40080
	s_addc_u32 s7, s7, 0
	s_add_u32 s46, s8, 0x100
	v_mov_b32_e32 v0, 0
	s_addc_u32 s47, s9, 0
	s_mov_b32 s49, -2
	s_waitcnt lgkmcnt(0)
	v_mov_b32_e32 v1, v0
	v_mov_b32_e32 v2, v0
	v_mov_b32_e32 v3, v0
	v_mov_b32_e32 v4, v0
	v_mov_b32_e32 v5, v0
	v_mov_b32_e32 v6, v0
	v_mov_b32_e32 v7, v0
	v_mov_b32_e32 v16, v0
	v_mov_b32_e32 v17, v0
	v_mov_b32_e32 v18, v0
	v_mov_b32_e32 v19, v0
	v_mov_b32_e32 v20, v0
	v_mov_b32_e32 v21, v0
	v_mov_b32_e32 v22, v0
	v_mov_b32_e32 v23, v0
	v_mov_b32_e32 v32, v0
	v_mov_b32_e32 v33, v0
	v_mov_b32_e32 v34, v0
	v_mov_b32_e32 v35, v0
	v_mov_b32_e32 v36, v0
	v_mov_b32_e32 v37, v0
	v_mov_b32_e32 v38, v0
	v_mov_b32_e32 v39, v0
	v_mov_b32_e32 v48, v0
	v_mov_b32_e32 v49, v0
	v_mov_b32_e32 v50, v0
	v_mov_b32_e32 v51, v0
	v_mov_b32_e32 v52, v0
	v_mov_b32_e32 v53, v0
	v_mov_b32_e32 v54, v0
	v_mov_b32_e32 v55, v0
	v_mov_b32_e32 v8, v0
	v_mov_b32_e32 v9, v0
	v_mov_b32_e32 v10, v0
	v_mov_b32_e32 v11, v0
	v_mov_b32_e32 v12, v0
	v_mov_b32_e32 v13, v0
	v_mov_b32_e32 v14, v0
	v_mov_b32_e32 v15, v0
	v_mov_b32_e32 v24, v0
	v_mov_b32_e32 v25, v0
	v_mov_b32_e32 v26, v0
	v_mov_b32_e32 v27, v0
	v_mov_b32_e32 v28, v0
	v_mov_b32_e32 v29, v0
	v_mov_b32_e32 v30, v0
	v_mov_b32_e32 v31, v0
	v_mov_b32_e32 v40, v0
	v_mov_b32_e32 v41, v0
	v_mov_b32_e32 v42, v0
	v_mov_b32_e32 v43, v0
	v_mov_b32_e32 v44, v0
	v_mov_b32_e32 v45, v0
	v_mov_b32_e32 v46, v0
	v_mov_b32_e32 v47, v0
	v_mov_b32_e32 v56, v0
	v_mov_b32_e32 v57, v0
	v_mov_b32_e32 v58, v0
	v_mov_b32_e32 v59, v0
	v_mov_b32_e32 v60, v0
	v_mov_b32_e32 v61, v0
	v_mov_b32_e32 v62, v0
	v_mov_b32_e32 v63, v0
	v_mov_b32_e32 v64, v0
	v_mov_b32_e32 v65, v0
	v_mov_b32_e32 v66, v0
	v_mov_b32_e32 v67, v0
	v_mov_b32_e32 v68, v0
	v_mov_b32_e32 v69, v0
	v_mov_b32_e32 v70, v0
	v_mov_b32_e32 v71, v0
	v_mov_b32_e32 v80, v0
	v_mov_b32_e32 v81, v0
	v_mov_b32_e32 v82, v0
	v_mov_b32_e32 v83, v0
	v_mov_b32_e32 v84, v0
	v_mov_b32_e32 v85, v0
	v_mov_b32_e32 v86, v0
	v_mov_b32_e32 v87, v0
	v_mov_b32_e32 v96, v0
	v_mov_b32_e32 v97, v0
	v_mov_b32_e32 v98, v0
	v_mov_b32_e32 v99, v0
	v_mov_b32_e32 v100, v0
	v_mov_b32_e32 v101, v0
	v_mov_b32_e32 v102, v0
	v_mov_b32_e32 v103, v0
	v_mov_b32_e32 v112, v0
	v_mov_b32_e32 v113, v0
	v_mov_b32_e32 v114, v0
	v_mov_b32_e32 v115, v0
	v_mov_b32_e32 v116, v0
	v_mov_b32_e32 v117, v0
	v_mov_b32_e32 v118, v0
	v_mov_b32_e32 v119, v0
	v_mov_b32_e32 v72, v0
	v_mov_b32_e32 v73, v0
	v_mov_b32_e32 v74, v0
	v_mov_b32_e32 v75, v0
	v_mov_b32_e32 v76, v0
	v_mov_b32_e32 v77, v0
	v_mov_b32_e32 v78, v0
	v_mov_b32_e32 v79, v0
	v_mov_b32_e32 v88, v0
	v_mov_b32_e32 v89, v0
	v_mov_b32_e32 v90, v0
	v_mov_b32_e32 v91, v0
	v_mov_b32_e32 v92, v0
	v_mov_b32_e32 v93, v0
	v_mov_b32_e32 v94, v0
	v_mov_b32_e32 v95, v0
	v_mov_b32_e32 v104, v0
	v_mov_b32_e32 v105, v0
	v_mov_b32_e32 v106, v0
	v_mov_b32_e32 v107, v0
	v_mov_b32_e32 v108, v0
	v_mov_b32_e32 v109, v0
	v_mov_b32_e32 v110, v0
	v_mov_b32_e32 v111, v0
	v_mov_b32_e32 v120, v0
	v_mov_b32_e32 v121, v0
	v_mov_b32_e32 v122, v0
	v_mov_b32_e32 v123, v0
	v_mov_b32_e32 v124, v0
	v_mov_b32_e32 v125, v0
	v_mov_b32_e32 v126, v0
	v_mov_b32_e32 v127, v0
	.p2align 3

; template <class Epi>
; DI void gemm_phase(PG8_LAS unsigned char* lds, const Gemm g, const StaticOrder& S, const Epi& E, const int wv) {
;     ...
; #pragma unroll
;     for (int a = 0; a < 2; ++a)
; #pragma unroll
;       for (int b = 0; b < 2; ++b)
; #pragma unroll
;         for (int m = 0; m < 4; ++m)
; #pragma unroll
;           for (int n = 0; n < 2; ++n) acc[a][b][m][n] = (f32x4){0.f, 0.f, 0.f, 0.f};
;     cur = nxt; cA = nA; cB = nB; ++ui;
.LBB0_520:
	s_add_u32 s55, s8, 0x100
	v_mov_b32_e32 v0, 0
	s_addc_u32 s57, s9, 0
	s_mov_b32 s58, -2
	v_mov_b32_e32 v1, v0
	v_mov_b32_e32 v2, v0
	v_mov_b32_e32 v3, v0
	v_mov_b32_e32 v4, v0
	v_mov_b32_e32 v5, v0
	v_mov_b32_e32 v6, v0
	v_mov_b32_e32 v7, v0
	v_mov_b32_e32 v8, v0
	v_mov_b32_e32 v9, v0
	v_mov_b32_e32 v10, v0
	v_mov_b32_e32 v11, v0
	v_mov_b32_e32 v16, v0
	v_mov_b32_e32 v17, v0
	v_mov_b32_e32 v18, v0
	v_mov_b32_e32 v19, v0
	v_mov_b32_e32 v24, v0
	v_mov_b32_e32 v25, v0
	v_mov_b32_e32 v26, v0
	v_mov_b32_e32 v27, v0
	v_mov_b32_e32 v28, v0
	v_mov_b32_e32 v29, v0
	v_mov_b32_e32 v30, v0
	v_mov_b32_e32 v31, v0
	v_mov_b32_e32 v36, v0
	v_mov_b32_e32 v37, v0
	v_mov_b32_e32 v38, v0
	v_mov_b32_e32 v39, v0
	v_mov_b32_e32 v40, v0
	v_mov_b32_e32 v41, v0
	v_mov_b32_e32 v42, v0
	v_mov_b32_e32 v43, v0
	v_mov_b32_e32 v12, v0
	v_mov_b32_e32 v13, v0
	v_mov_b32_e32 v14, v0
	v_mov_b32_e32 v15, v0
	v_mov_b32_e32 v20, v0
	v_mov_b32_e32 v21, v0
	v_mov_b32_e32 v22, v0
	v_mov_b32_e32 v23, v0
	v_mov_b32_e32 v32, v0
	v_mov_b32_e32 v33, v0
	v_mov_b32_e32 v34, v0
	v_mov_b32_e32 v35, v0
	v_mov_b32_e32 v44, v0
	v_mov_b32_e32 v45, v0
	v_mov_b32_e32 v46, v0
	v_mov_b32_e32 v47, v0
	v_mov_b32_e32 v48, v0
	v_mov_b32_e32 v49, v0
	v_mov_b32_e32 v50, v0
	v_mov_b32_e32 v51, v0
	v_mov_b32_e32 v52, v0
	v_mov_b32_e32 v53, v0
	v_mov_b32_e32 v54, v0
	v_mov_b32_e32 v55, v0
	v_mov_b32_e32 v56, v0
	v_mov_b32_e32 v57, v0
	v_mov_b32_e32 v58, v0
	v_mov_b32_e32 v59, v0
	v_mov_b32_e32 v60, v0
	v_mov_b32_e32 v61, v0
	v_mov_b32_e32 v62, v0
	v_mov_b32_e32 v63, v0
	v_mov_b32_e32 v64, v0
	v_mov_b32_e32 v65, v0
	v_mov_b32_e32 v66, v0
	v_mov_b32_e32 v67, v0
	v_mov_b32_e32 v68, v0
	v_mov_b32_e32 v69, v0
	v_mov_b32_e32 v70, v0
	v_mov_b32_e32 v71, v0
	v_mov_b32_e32 v72, v0
	v_mov_b32_e32 v73, v0
	v_mov_b32_e32 v74, v0
	v_mov_b32_e32 v75, v0
	v_mov_b32_e32 v80, v0
	v_mov_b32_e32 v81, v0
	v_mov_b32_e32 v82, v0
	v_mov_b32_e32 v83, v0
	v_mov_b32_e32 v88, v0
	v_mov_b32_e32 v89, v0
	v_mov_b32_e32 v90, v0
	v_mov_b32_e32 v91, v0
	v_mov_b32_e32 v92, v0
	v_mov_b32_e32 v93, v0
	v_mov_b32_e32 v94, v0
	v_mov_b32_e32 v95, v0
	v_mov_b32_e32 v104, v0
	v_mov_b32_e32 v105, v0
	v_mov_b32_e32 v106, v0
	v_mov_b32_e32 v107, v0
	v_mov_b32_e32 v108, v0
	v_mov_b32_e32 v109, v0
	v_mov_b32_e32 v110, v0
	v_mov_b32_e32 v111, v0
	v_mov_b32_e32 v76, v0
	v_mov_b32_e32 v77, v0
	v_mov_b32_e32 v78, v0
	v_mov_b32_e32 v79, v0
	v_mov_b32_e32 v84, v0
	v_mov_b32_e32 v85, v0
	v_mov_b32_e32 v86, v0
	v_mov_b32_e32 v87, v0
	v_mov_b32_e32 v96, v0
	v_mov_b32_e32 v97, v0
	v_mov_b32_e32 v98, v0
	v_mov_b32_e32 v99, v0
	v_mov_b32_e32 v100, v0
	v_mov_b32_e32 v101, v0
	v_mov_b32_e32 v102, v0
	v_mov_b32_e32 v103, v0
	v_mov_b32_e32 v112, v0
	v_mov_b32_e32 v113, v0
	v_mov_b32_e32 v114, v0
	v_mov_b32_e32 v115, v0
	v_mov_b32_e32 v116, v0
	v_mov_b32_e32 v117, v0
	v_mov_b32_e32 v118, v0
	v_mov_b32_e32 v119, v0
	v_mov_b32_e32 v120, v0
	v_mov_b32_e32 v121, v0
	v_mov_b32_e32 v122, v0
	v_mov_b32_e32 v123, v0
	v_mov_b32_e32 v124, v0
	v_mov_b32_e32 v125, v0
	v_mov_b32_e32 v126, v0
	v_mov_b32_e32 v127, v0
	.p2align 3

; template <class Epi>
; DI void gemm_phase(PG8_LAS unsigned char* lds, const Gemm g, const StaticOrder& S, const Epi& E, const int wv) {
;     ...
;     const bool has_next = S.next(ui + 1, nxt);
;     const char* nA = has_next ? (const char*)g.A + (size_t)nxt.pm * tstep : cA; const char* nB = has_next ? (const char*)g.Bt + (size_t)nxt.pn * tstep : cB;
;     ...
; #pragma unroll
;     for (int a = 0; a < 2; ++a)
; #pragma unroll
;       for (int b = 0; b < 2; ++b)
; #pragma unroll
;         for (int m = 0; m < 4; ++m)
; #pragma unroll
;           for (int n = 0; n < 2; ++n) acc[a][b][m][n] = (f32x4){0.f, 0.f, 0.f, 0.f};
;     cur = nxt; cA = nA; cB = nB; ++ui;
.LBB0_536:
	s_ashr_i32 s27, s26, 31
	s_lshl_b64 s[28:29], s[26:27], 17
	s_add_u32 s28, s52, s28
	s_addc_u32 s29, s53, s29
	s_and_b64 s[30:31], exec, s[22:23]
	s_cselect_b32 s5, s9, s29
	s_cselect_b32 s27, s8, s28
	s_ashr_i32 s25, s24, 31
	s_lshl_b64 s[30:31], s[24:25], 17
	s_add_u32 s30, s54, s30
	s_addc_u32 s31, s55, s31
	s_and_b64 s[36:37], exec, s[22:23]
	v_mov_b32_e32 v0, 0
	s_cselect_b32 s25, s7, s31
	s_cselect_b32 s35, s6, s30
	s_mov_b64 s[40:41], 0
	s_mov_b64 s[36:37], -1
	s_mov_b64 s[38:39], 0
	v_mov_b32_e32 v1, v0
	v_mov_b32_e32 v2, v0
	v_mov_b32_e32 v3, v0
	v_mov_b32_e32 v4, v0
	v_mov_b32_e32 v5, v0
	v_mov_b32_e32 v6, v0
	v_mov_b32_e32 v7, v0
	v_mov_b32_e32 v8, v0
	v_mov_b32_e32 v9, v0
	v_mov_b32_e32 v10, v0
	v_mov_b32_e32 v11, v0
	v_mov_b32_e32 v20, v0
	v_mov_b32_e32 v21, v0
	v_mov_b32_e32 v22, v0
	v_mov_b32_e32 v23, v0
	v_mov_b32_e32 v24, v0
	v_mov_b32_e32 v25, v0
	v_mov_b32_e32 v26, v0
	v_mov_b32_e32 v27, v0
	v_mov_b32_e32 v36, v0
	v_mov_b32_e32 v37, v0
	v_mov_b32_e32 v38, v0
	v_mov_b32_e32 v39, v0
	v_mov_b32_e32 v40, v0
	v_mov_b32_e32 v41, v0
	v_mov_b32_e32 v42, v0
	v_mov_b32_e32 v43, v0
	v_mov_b32_e32 v52, v0
	v_mov_b32_e32 v53, v0
	v_mov_b32_e32 v54, v0
	v_mov_b32_e32 v55, v0
	v_mov_b32_e32 v12, v0
	v_mov_b32_e32 v13, v0
	v_mov_b32_e32 v14, v0
	v_mov_b32_e32 v15, v0
	v_mov_b32_e32 v16, v0
	v_mov_b32_e32 v17, v0
	v_mov_b32_e32 v18, v0
	v_mov_b32_e32 v19, v0
	v_mov_b32_e32 v28, v0
	v_mov_b32_e32 v29, v0
	v_mov_b32_e32 v30, v0
	v_mov_b32_e32 v31, v0
	v_mov_b32_e32 v32, v0
	v_mov_b32_e32 v33, v0
	v_mov_b32_e32 v34, v0
	v_mov_b32_e32 v35, v0
	v_mov_b32_e32 v44, v0
	v_mov_b32_e32 v45, v0
	v_mov_b32_e32 v46, v0
	v_mov_b32_e32 v47, v0
	v_mov_b32_e32 v48, v0
	v_mov_b32_e32 v49, v0
	v_mov_b32_e32 v50, v0
	v_mov_b32_e32 v51, v0
	v_mov_b32_e32 v56, v0
	v_mov_b32_e32 v57, v0
	v_mov_b32_e32 v58, v0
	v_mov_b32_e32 v59, v0
	v_mov_b32_e32 v60, v0
	v_mov_b32_e32 v61, v0
	v_mov_b32_e32 v62, v0
	v_mov_b32_e32 v63, v0
	v_mov_b32_e32 v64, v0
	v_mov_b32_e32 v65, v0
	v_mov_b32_e32 v66, v0
	v_mov_b32_e32 v67, v0
	v_mov_b32_e32 v68, v0
	v_mov_b32_e32 v69, v0
	v_mov_b32_e32 v70, v0
	v_mov_b32_e32 v71, v0
	v_mov_b32_e32 v72, v0
	v_mov_b32_e32 v73, v0
	v_mov_b32_e32 v74, v0
	v_mov_b32_e32 v75, v0
	v_mov_b32_e32 v84, v0
	v_mov_b32_e32 v85, v0
	v_mov_b32_e32 v86, v0
	v_mov_b32_e32 v87, v0
	v_mov_b32_e32 v88, v0
	v_mov_b32_e32 v89, v0
	v_mov_b32_e32 v90, v0
	v_mov_b32_e32 v91, v0
	v_mov_b32_e32 v100, v0
	v_mov_b32_e32 v101, v0
	v_mov_b32_e32 v102, v0
	v_mov_b32_e32 v103, v0
	v_mov_b32_e32 v104, v0
	v_mov_b32_e32 v105, v0
	v_mov_b32_e32 v106, v0
	v_mov_b32_e32 v107, v0
	v_mov_b32_e32 v116, v0
	v_mov_b32_e32 v117, v0
	v_mov_b32_e32 v118, v0
	v_mov_b32_e32 v119, v0
	v_mov_b32_e32 v76, v0
	v_mov_b32_e32 v77, v0
	v_mov_b32_e32 v78, v0
	v_mov_b32_e32 v79, v0
	v_mov_b32_e32 v80, v0
	v_mov_b32_e32 v81, v0
	v_mov_b32_e32 v82, v0
	v_mov_b32_e32 v83, v0
	v_mov_b32_e32 v92, v0
	v_mov_b32_e32 v93, v0
	v_mov_b32_e32 v94, v0
	v_mov_b32_e32 v95, v0
	v_mov_b32_e32 v96, v0
	v_mov_b32_e32 v97, v0
	v_mov_b32_e32 v98, v0
	v_mov_b32_e32 v99, v0
	v_mov_b32_e32 v108, v0
	v_mov_b32_e32 v109, v0
	v_mov_b32_e32 v110, v0
	v_mov_b32_e32 v111, v0
	v_mov_b32_e32 v112, v0
	v_mov_b32_e32 v113, v0
	v_mov_b32_e32 v114, v0
	v_mov_b32_e32 v115, v0
	v_mov_b32_e32 v120, v0
	v_mov_b32_e32 v121, v0
	v_mov_b32_e32 v122, v0
	v_mov_b32_e32 v123, v0
	v_mov_b32_e32 v124, v0
	v_mov_b32_e32 v125, v0
	v_mov_b32_e32 v126, v0
	v_mov_b32_e32 v127, v0
	.p2align 3

; #define RAW_BAR() do { asm volatile("s_waitcnt lgkmcnt(0)" ::: "memory"); __builtin_amdgcn_s_barrier(); asm volatile("" ::: "memory"); } while (0)
; #define A_DECODE(it_, hq_, sq_, q0_, ql_) do { if ((it_) < NF) { hq_ = ((it_) >> 4) % NHQ; sq_ = (it_) / (16 * NHQ); q0_ = NMETA + 256 * ((it_) & 15); ql_ = L; } \
;     else { const int tt_ = (it_) - NF; hq_ = tt_ % NHQ; sq_ = tt_ / NHQ; q0_ = 0; ql_ = NMETA; } } while (0)
; #define A_LOADK(Kb_, tile_) do { const char* kp_ = (const char*)(Kb_) + (size_t)(tile_) * (64 * LDK * 2); const unsigned ko_ = ((tile_) == NT - 1) ? koffL : koff; \
;     _Pragma("unroll") for (int i_ = 0; i_ < NKC; ++i_) rk[i_] = *(const u32x4*)(kp_ + ko_ + i_ * 128); } while (0)
; #define A_LOADV(Vb_, tile_) do { const char* vp_ = (const char*)(Vb_) + (size_t)(tile_) * 128; \
;     rv[0] = *(const u32x4*)(vp_ + voff); rv[1] = *(const u32x4*)(vp_ + voff + 64 * LP * 2); } while (0)
; #define A_WRITEK(bi_) do { char* b_ = kb0 + (bi_) * KBYTES + kwoff; \
;     _Pragma("unroll") for (int i_ = 0; i_ < NKC; ++i_) *(u32x4*)(b_ + i_ * 128) = rk[i_]; } while (0)
; #define A_WRITEV(bi_) do { char* b_ = vb0 + (bi_) * VBYTES + vwoff; \
;     *(u32x4*)(b_) = rv[0]; *(u32x4*)(b_ + 64 * VSTR) = rv[1]; } while (0)
; template <int DQK, int NHQ, int NHKV, bool HAS_META>
; DI void attn_phase(const u16* __restrict__ Q, const u16* __restrict__ K, const u16* __restrict__ Vt, u16* __restrict__ O, const float* __restrict__ qg, const float* __restrict__ kg, char* smem, const int wv) {
;     ...
;     l = 0.f;
; #pragma unroll
;     for (int d = 0; d < 4; ++d)
; #pragma unroll
;       for (int i = 0; i < 16; ++i) o[d][i] = 0.f;
;     const int nitem = item + (int)gridDim.x;
;     const bool has_next = nitem < nItems;
;     int nhq, nsq, nq0, nqlim;
;     A_DECODE(nitem, nhq, nsq, nq0, nqlim);
;     const u16* nKb = K + (size_t)(nsq * L) * LDK + (nhq / (NHQ / NHKV)) * DQK;
;     const u16* nVb = Vt + (size_t)((nsq * NHKV + nhq / (NHQ / NHKV)) * 128) * LP;
;     RAW_BAR();
;     A_WRITEK(1); A_WRITEV(0);
;     __builtin_amdgcn_sched_barrier(0);
;     if (active) A_QK(0);
;     __builtin_amdgcn_sched_barrier(0);
;     A_LOADK(Kb, 2); A_LOADV(Vb, 1);
;     RAW_BAR();
;     for (int j = 0; j < NT; ++j) {
.LBB0_675:
	s_mul_i32 s4, s43, 0x1010
	s_mul_hi_i32 s25, s4, 0x600
	s_mul_i32 s4, s55, 0xc0
	s_mul_i32 s24, s43, 0x606000
	s_ashr_i32 s5, s4, 31
	s_add_u32 s24, s44, s24
	s_addc_u32 s25, s45, s25
	s_lshl_b64 s[4:5], s[4:5], 1
	s_add_u32 s24, s24, s4
	s_addc_u32 s25, s25, s5
	s_cmpk_lt_i32 s54, 0x660
	s_cselect_b64 s[28:29], -1, 0
	s_cmpk_gt_i32 s54, 0x65f
	s_cselect_b64 s[26:27], -1, 0
	v_lshl_add_u64 v[2:3], s[6:7], 0, v[196:197]
	v_lshl_add_u64 v[4:5], v[2:3], 0, s[20:21]
	v_add_co_u32_e32 v2, vcc, s51, v2
	v_mov_b32_e32 v14, v1
	s_nop 0
	v_addc_co_u32_e32 v3, vcc, 0, v3, vcc
	global_load_dwordx4 v[116:119], v[2:3], off
	global_load_dwordx4 v[120:123], v[4:5], off offset:128
	global_load_dwordx4 v[124:127], v[4:5], off offset:256
	v_lshl_add_u64 v[2:3], s[34:35], 0, v[198:199]
	v_add_co_u32_e32 v4, vcc, s50, v2
	v_mov_b32_e32 v15, v1
	s_nop 0
	v_addc_co_u32_e32 v5, vcc, 0, v3, vcc
	global_load_dwordx4 v[140:143], v[2:3], off offset:128
	global_load_dwordx4 v[144:147], v[4:5], off offset:128
	s_waitcnt lgkmcnt(0)
	s_barrier
	v_mov_b32_e32 v0, v1
	v_mov_b32_e32 v2, v1
	v_mov_b32_e32 v3, v1
	v_mov_b32_e32 v4, v1
	v_mov_b32_e32 v5, v1
	v_mov_b32_e32 v6, v1
	v_mov_b32_e32 v7, v1
	v_mov_b32_e32 v8, v1
	v_mov_b32_e32 v9, v1
	v_mov_b32_e32 v10, v1
	v_mov_b32_e32 v11, v1
	v_mov_b32_e32 v12, v1
	v_mov_b32_e32 v13, v1
	v_mov_b64_e32 v[110:111], v[14:15]
	v_mov_b64_e32 v[94:95], v[14:15]
	v_mov_b64_e32 v[78:79], v[14:15]
	v_mov_b64_e32 v[62:63], v[14:15]
	s_mov_b32 s59, 0
	v_lshl_add_u64 v[208:209], s[24:25], 0, v[196:197]
	v_lshl_add_u64 v[210:211], s[34:35], 0, v[200:201]
	v_mov_b32_e32 v221, 0
	s_mov_b64 s[34:35], 0
	s_xor_b64 s[36:37], s[28:29], -1
	v_mov_b64_e32 v[108:109], v[12:13]
	v_mov_b64_e32 v[106:107], v[10:11]
	v_mov_b64_e32 v[104:105], v[8:9]
	v_mov_b64_e32 v[102:103], v[6:7]
	v_mov_b64_e32 v[100:101], v[4:5]
	v_mov_b64_e32 v[98:99], v[2:3]
	v_mov_b64_e32 v[96:97], v[0:1]
	v_mov_b64_e32 v[92:93], v[12:13]
	v_mov_b64_e32 v[90:91], v[10:11]
	v_mov_b64_e32 v[88:89], v[8:9]
	v_mov_b64_e32 v[86:87], v[6:7]
	v_mov_b64_e32 v[84:85], v[4:5]
	v_mov_b64_e32 v[82:83], v[2:3]
	v_mov_b64_e32 v[80:81], v[0:1]
	v_mov_b64_e32 v[76:77], v[12:13]
	v_mov_b64_e32 v[74:75], v[10:11]
	v_mov_b64_e32 v[72:73], v[8:9]
	v_mov_b64_e32 v[70:71], v[6:7]
	v_mov_b64_e32 v[68:69], v[4:5]
	v_mov_b64_e32 v[66:67], v[2:3]
	v_mov_b64_e32 v[64:65], v[0:1]
	v_mov_b64_e32 v[60:61], v[12:13]
	v_mov_b64_e32 v[58:59], v[10:11]
	v_mov_b64_e32 v[56:57], v[8:9]
	v_mov_b64_e32 v[54:55], v[6:7]
	v_mov_b64_e32 v[52:53], v[4:5]
	v_mov_b64_e32 v[50:51], v[2:3]
	v_mov_b64_e32 v[48:49], v[0:1]
	.p2align 3

; template <class Epi>
; DI void gemm_phase(PG8_LAS unsigned char* lds, const Gemm g, const StaticOrder& S, const Epi& E, const int wv) {
;     ...
;     const bool has_next = S.next(ui + 1, nxt);
;     const char* nA = has_next ? (const char*)g.A + (size_t)nxt.pm * tstep : cA; const char* nB = has_next ? (const char*)g.Bt + (size_t)nxt.pn * tstep : cB;
;     ...
; #pragma unroll
;     for (int a = 0; a < 2; ++a)
; #pragma unroll
;       for (int b = 0; b < 2; ++b)
; #pragma unroll
;         for (int m = 0; m < 4; ++m)
; #pragma unroll
;           for (int n = 0; n < 2; ++n) acc[a][b][m][n] = (f32x4){0.f, 0.f, 0.f, 0.f};
;     cur = nxt; cA = nA; cB = nB; ++ui;
.LBB0_769:
	s_ashr_i32 s29, s28, 31
	s_lshl_b64 s[30:31], s[28:29], 19
	s_add_u32 s30, s48, s30
	s_addc_u32 s31, s49, s31
	s_and_b64 s[34:35], exec, s[24:25]
	s_cselect_b32 s29, s41, s31
	s_cselect_b32 s37, s40, s30
	s_ashr_i32 s27, s26, 31
	s_lshl_b64 s[34:35], s[26:27], 19
	s_add_u32 s34, s50, s34
	s_addc_u32 s35, s51, s35
	s_and_b64 s[44:45], exec, s[24:25]
	s_cselect_b32 s27, s43, s35
	s_cselect_b32 s39, s42, s34
	s_add_u32 s40, s40, 0x40080
	s_addc_u32 s41, s41, 0
	s_add_u32 s74, s42, 0x100
	v_mov_b32_e32 v0, 0
	s_addc_u32 s75, s43, 0
	s_mov_b32 s76, -2
	s_waitcnt lgkmcnt(0)
	v_mov_b32_e32 v1, v0
	v_mov_b32_e32 v2, v0
	v_mov_b32_e32 v3, v0
	v_mov_b32_e32 v4, v0
	v_mov_b32_e32 v5, v0
	v_mov_b32_e32 v6, v0
	v_mov_b32_e32 v7, v0
	v_mov_b32_e32 v16, v0
	v_mov_b32_e32 v17, v0
	v_mov_b32_e32 v18, v0
	v_mov_b32_e32 v19, v0
	v_mov_b32_e32 v20, v0
	v_mov_b32_e32 v21, v0
	v_mov_b32_e32 v22, v0
	v_mov_b32_e32 v23, v0
	v_mov_b32_e32 v32, v0
	v_mov_b32_e32 v33, v0
	v_mov_b32_e32 v34, v0
	v_mov_b32_e32 v35, v0
	v_mov_b32_e32 v36, v0
	v_mov_b32_e32 v37, v0
	v_mov_b32_e32 v38, v0
	v_mov_b32_e32 v39, v0
	v_mov_b32_e32 v48, v0
	v_mov_b32_e32 v49, v0
	v_mov_b32_e32 v50, v0
	v_mov_b32_e32 v51, v0
	v_mov_b32_e32 v52, v0
	v_mov_b32_e32 v53, v0
	v_mov_b32_e32 v54, v0
	v_mov_b32_e32 v55, v0
	v_mov_b32_e32 v8, v0
	v_mov_b32_e32 v9, v0
	v_mov_b32_e32 v10, v0
	v_mov_b32_e32 v11, v0
	v_mov_b32_e32 v12, v0
	v_mov_b32_e32 v13, v0
	v_mov_b32_e32 v14, v0
	v_mov_b32_e32 v15, v0
	v_mov_b32_e32 v24, v0
	v_mov_b32_e32 v25, v0
	v_mov_b32_e32 v26, v0
	v_mov_b32_e32 v27, v0
	v_mov_b32_e32 v28, v0
	v_mov_b32_e32 v29, v0
	v_mov_b32_e32 v30, v0
	v_mov_b32_e32 v31, v0
	v_mov_b32_e32 v40, v0
	v_mov_b32_e32 v41, v0
	v_mov_b32_e32 v42, v0
	v_mov_b32_e32 v43, v0
	v_mov_b32_e32 v44, v0
	v_mov_b32_e32 v45, v0
	v_mov_b32_e32 v46, v0
	v_mov_b32_e32 v47, v0
	v_mov_b32_e32 v56, v0
	v_mov_b32_e32 v57, v0
	v_mov_b32_e32 v58, v0
	v_mov_b32_e32 v59, v0
	v_mov_b32_e32 v60, v0
	v_mov_b32_e32 v61, v0
	v_mov_b32_e32 v62, v0
	v_mov_b32_e32 v63, v0
	v_mov_b32_e32 v64, v0
	v_mov_b32_e32 v65, v0
	v_mov_b32_e32 v66, v0
	v_mov_b32_e32 v67, v0
	v_mov_b32_e32 v68, v0
	v_mov_b32_e32 v69, v0
	v_mov_b32_e32 v70, v0
	v_mov_b32_e32 v71, v0
	v_mov_b32_e32 v80, v0
	v_mov_b32_e32 v81, v0
	v_mov_b32_e32 v82, v0
	v_mov_b32_e32 v83, v0
	v_mov_b32_e32 v84, v0
	v_mov_b32_e32 v85, v0
	v_mov_b32_e32 v86, v0
	v_mov_b32_e32 v87, v0
	v_mov_b32_e32 v96, v0
	v_mov_b32_e32 v97, v0
	v_mov_b32_e32 v98, v0
	v_mov_b32_e32 v99, v0
	v_mov_b32_e32 v100, v0
	v_mov_b32_e32 v101, v0
	v_mov_b32_e32 v102, v0
	v_mov_b32_e32 v103, v0
	v_mov_b32_e32 v112, v0
	v_mov_b32_e32 v113, v0
	v_mov_b32_e32 v114, v0
	v_mov_b32_e32 v115, v0
	s_waitcnt vmcnt(0)
	v_mov_b32_e32 v116, v0
	v_mov_b32_e32 v117, v0
	v_mov_b32_e32 v118, v0
	v_mov_b32_e32 v119, v0
	v_mov_b32_e32 v72, v0
	v_mov_b32_e32 v73, v0
	v_mov_b32_e32 v74, v0
	v_mov_b32_e32 v75, v0
	v_mov_b32_e32 v76, v0
	v_mov_b32_e32 v77, v0
	v_mov_b32_e32 v78, v0
	v_mov_b32_e32 v79, v0
	v_mov_b32_e32 v88, v0
	v_mov_b32_e32 v89, v0
	v_mov_b32_e32 v90, v0
	v_mov_b32_e32 v91, v0
	v_mov_b32_e32 v92, v0
	v_mov_b32_e32 v93, v0
	v_mov_b32_e32 v94, v0
	v_mov_b32_e32 v95, v0
	v_mov_b32_e32 v104, v0
	v_mov_b32_e32 v105, v0
	v_mov_b32_e32 v106, v0
	v_mov_b32_e32 v107, v0
	v_mov_b32_e32 v108, v0
	v_mov_b32_e32 v109, v0
	v_mov_b32_e32 v110, v0
	v_mov_b32_e32 v111, v0
	v_mov_b32_e32 v120, v0
	v_mov_b32_e32 v121, v0
	v_mov_b32_e32 v122, v0
	v_mov_b32_e32 v123, v0
	v_mov_b32_e32 v124, v0
	v_mov_b32_e32 v125, v0
	v_mov_b32_e32 v126, v0
	v_mov_b32_e32 v127, v0
	.p2align 3

; template <class Epi>
; DI void gemm_phase(PG8_LAS unsigned char* lds, const Gemm g, const StaticOrder& S, const Epi& E, const int wv) {
;     ...
;     const bool has_next = S.next(ui + 1, nxt);
;     const char* nA = has_next ? (const char*)g.A + (size_t)nxt.pm * tstep : cA; const char* nB = has_next ? (const char*)g.Bt + (size_t)nxt.pn * tstep : cB;
;     ...
; #pragma unroll
;     for (int a = 0; a < 2; ++a)
; #pragma unroll
;       for (int b = 0; b < 2; ++b)
; #pragma unroll
;         for (int m = 0; m < 4; ++m)
; #pragma unroll
;           for (int n = 0; n < 2; ++n) acc[a][b][m][n] = (f32x4){0.f, 0.f, 0.f, 0.f};
;     cur = nxt; cA = nA; cB = nB; ++ui;
.LBB0_892:
	s_ashr_i32 s27, s26, 31
	s_lshl_b64 s[28:29], s[26:27], 19
	s_add_u32 s28, s41, s28
	s_addc_u32 s29, s42, s29
	s_and_b64 s[30:31], exec, s[22:23]
	s_cselect_b32 s5, s7, s29
	s_cselect_b32 s27, s6, s28
	s_ashr_i32 s25, s24, 31
	s_lshl_b64 s[30:31], s[24:25], 19
	s_add_u32 s30, s43, s30
	s_addc_u32 s31, s44, s31
	s_and_b64 s[36:37], exec, s[22:23]
	s_cselect_b32 s25, s9, s31
	s_cselect_b32 s59, s8, s30
	s_add_u32 s6, s6, 0x40080
	s_addc_u32 s7, s7, 0
	s_add_u32 s60, s8, 0x100
	v_mov_b32_e32 v0, 0
	s_addc_u32 s61, s9, 0
	s_mov_b32 s62, -2
	v_mov_b32_e32 v1, v0
	v_mov_b32_e32 v2, v0
	v_mov_b32_e32 v3, v0
	v_mov_b32_e32 v8, v0
	v_mov_b32_e32 v9, v0
	v_mov_b32_e32 v10, v0
	v_mov_b32_e32 v11, v0
	v_mov_b32_e32 v16, v0
	v_mov_b32_e32 v17, v0
	v_mov_b32_e32 v18, v0
	v_mov_b32_e32 v19, v0
	v_mov_b32_e32 v24, v0
	v_mov_b32_e32 v25, v0
	v_mov_b32_e32 v26, v0
	v_mov_b32_e32 v27, v0
	v_mov_b32_e32 v32, v0
	v_mov_b32_e32 v33, v0
	v_mov_b32_e32 v34, v0
	v_mov_b32_e32 v35, v0
	v_mov_b32_e32 v40, v0
	v_mov_b32_e32 v41, v0
	v_mov_b32_e32 v42, v0
	v_mov_b32_e32 v43, v0
	v_mov_b32_e32 v56, v0
	v_mov_b32_e32 v57, v0
	v_mov_b32_e32 v58, v0
	v_mov_b32_e32 v59, v0
	v_mov_b32_e32 v60, v0
	v_mov_b32_e32 v61, v0
	v_mov_b32_e32 v62, v0
	v_mov_b32_e32 v63, v0
	v_mov_b32_e32 v4, v0
	v_mov_b32_e32 v5, v0
	v_mov_b32_e32 v6, v0
	v_mov_b32_e32 v7, v0
	v_mov_b32_e32 v12, v0
	v_mov_b32_e32 v13, v0
	v_mov_b32_e32 v14, v0
	v_mov_b32_e32 v15, v0
	v_mov_b32_e32 v20, v0
	v_mov_b32_e32 v21, v0
	v_mov_b32_e32 v22, v0
	v_mov_b32_e32 v23, v0
	v_mov_b32_e32 v28, v0
	v_mov_b32_e32 v29, v0
	v_mov_b32_e32 v30, v0
	v_mov_b32_e32 v31, v0
	v_mov_b32_e32 v36, v0
	v_mov_b32_e32 v37, v0
	v_mov_b32_e32 v38, v0
	v_mov_b32_e32 v39, v0
	v_mov_b32_e32 v44, v0
	v_mov_b32_e32 v45, v0
	v_mov_b32_e32 v46, v0
	v_mov_b32_e32 v47, v0
	v_mov_b32_e32 v48, v0
	v_mov_b32_e32 v49, v0
	v_mov_b32_e32 v50, v0
	v_mov_b32_e32 v51, v0
	v_mov_b32_e32 v52, v0
	v_mov_b32_e32 v53, v0
	v_mov_b32_e32 v54, v0
	v_mov_b32_e32 v55, v0
	v_mov_b32_e32 v64, v0
	v_mov_b32_e32 v65, v0
	v_mov_b32_e32 v66, v0
	v_mov_b32_e32 v67, v0
	v_mov_b32_e32 v72, v0
	v_mov_b32_e32 v73, v0
	v_mov_b32_e32 v74, v0
	v_mov_b32_e32 v75, v0
	v_mov_b32_e32 v80, v0
	v_mov_b32_e32 v81, v0
	v_mov_b32_e32 v82, v0
	v_mov_b32_e32 v83, v0
	v_mov_b32_e32 v88, v0
	v_mov_b32_e32 v89, v0
	v_mov_b32_e32 v90, v0
	v_mov_b32_e32 v91, v0
	v_mov_b32_e32 v96, v0
	v_mov_b32_e32 v97, v0
	v_mov_b32_e32 v98, v0
	v_mov_b32_e32 v99, v0
	v_mov_b32_e32 v104, v0
	v_mov_b32_e32 v105, v0
	v_mov_b32_e32 v106, v0
	v_mov_b32_e32 v107, v0
	v_mov_b32_e32 v120, v0
	v_mov_b32_e32 v121, v0
	v_mov_b32_e32 v122, v0
	v_mov_b32_e32 v123, v0
	v_mov_b32_e32 v124, v0
	v_mov_b32_e32 v125, v0
	v_mov_b32_e32 v126, v0
	v_mov_b32_e32 v127, v0
	v_mov_b32_e32 v68, v0
	v_mov_b32_e32 v69, v0
	v_mov_b32_e32 v70, v0
	v_mov_b32_e32 v71, v0
	v_mov_b32_e32 v76, v0
	v_mov_b32_e32 v77, v0
	v_mov_b32_e32 v78, v0
	v_mov_b32_e32 v79, v0
	v_mov_b32_e32 v84, v0
	v_mov_b32_e32 v85, v0
	v_mov_b32_e32 v86, v0
	v_mov_b32_e32 v87, v0
	v_mov_b32_e32 v92, v0
	v_mov_b32_e32 v93, v0
	v_mov_b32_e32 v94, v0
	v_mov_b32_e32 v95, v0
	v_mov_b32_e32 v100, v0
	v_mov_b32_e32 v101, v0
	v_mov_b32_e32 v102, v0
	v_mov_b32_e32 v103, v0
	v_mov_b32_e32 v108, v0
	v_mov_b32_e32 v109, v0
	v_mov_b32_e32 v110, v0
	v_mov_b32_e32 v111, v0
	v_mov_b32_e32 v112, v0
	v_mov_b32_e32 v113, v0
	v_mov_b32_e32 v114, v0
	v_mov_b32_e32 v115, v0
	v_mov_b32_e32 v116, v0
	v_mov_b32_e32 v117, v0
	v_mov_b32_e32 v118, v0
	v_mov_b32_e32 v119, v0
	.p2align 3

; template <class Epi>
; DI void gemm_phase(PG8_LAS unsigned char* lds, const Gemm g, const StaticOrder& S, const Epi& E, const int wv) {
;     ...
; #pragma unroll
;     for (int a = 0; a < 2; ++a)
; #pragma unroll
;       for (int b = 0; b < 2; ++b)
; #pragma unroll
;         for (int m = 0; m < 4; ++m)
; #pragma unroll
;           for (int n = 0; n < 2; ++n) acc[a][b][m][n] = (f32x4){0.f, 0.f, 0.f, 0.f};
;     cur = nxt; cA = nA; cB = nB; ++ui;
.LBB0_967:
	s_add_u32 s61, s28, 0x100
	v_mov_b32_e32 v0, 0
	s_addc_u32 s62, s29, 0
	s_mov_b32 s63, -2
	s_waitcnt lgkmcnt(0)
	v_mov_b32_e32 v1, v0
	v_mov_b32_e32 v2, v0
	v_mov_b32_e32 v3, v0
	v_mov_b32_e32 v4, v0
	v_mov_b32_e32 v5, v0
	v_mov_b32_e32 v6, v0
	v_mov_b32_e32 v7, v0
	v_mov_b32_e32 v16, v0
	v_mov_b32_e32 v17, v0
	v_mov_b32_e32 v18, v0
	v_mov_b32_e32 v19, v0
	v_mov_b32_e32 v20, v0
	v_mov_b32_e32 v21, v0
	v_mov_b32_e32 v22, v0
	v_mov_b32_e32 v23, v0
	v_mov_b32_e32 v32, v0
	v_mov_b32_e32 v33, v0
	v_mov_b32_e32 v34, v0
	v_mov_b32_e32 v35, v0
	v_mov_b32_e32 v36, v0
	v_mov_b32_e32 v37, v0
	v_mov_b32_e32 v38, v0
	v_mov_b32_e32 v39, v0
	v_mov_b32_e32 v48, v0
	v_mov_b32_e32 v49, v0
	v_mov_b32_e32 v50, v0
	v_mov_b32_e32 v51, v0
	v_mov_b32_e32 v52, v0
	v_mov_b32_e32 v53, v0
	v_mov_b32_e32 v54, v0
	v_mov_b32_e32 v55, v0
	v_mov_b32_e32 v8, v0
	v_mov_b32_e32 v9, v0
	v_mov_b32_e32 v10, v0
	v_mov_b32_e32 v11, v0
	v_mov_b32_e32 v12, v0
	v_mov_b32_e32 v13, v0
	v_mov_b32_e32 v14, v0
	v_mov_b32_e32 v15, v0
	v_mov_b32_e32 v24, v0
	v_mov_b32_e32 v25, v0
	v_mov_b32_e32 v26, v0
	v_mov_b32_e32 v27, v0
	v_mov_b32_e32 v28, v0
	v_mov_b32_e32 v29, v0
	v_mov_b32_e32 v30, v0
	v_mov_b32_e32 v31, v0
	v_mov_b32_e32 v40, v0
	v_mov_b32_e32 v41, v0
	v_mov_b32_e32 v42, v0
	v_mov_b32_e32 v43, v0
	v_mov_b32_e32 v44, v0
	v_mov_b32_e32 v45, v0
	v_mov_b32_e32 v46, v0
	v_mov_b32_e32 v47, v0
	v_mov_b32_e32 v56, v0
	v_mov_b32_e32 v57, v0
	v_mov_b32_e32 v58, v0
	v_mov_b32_e32 v59, v0
	v_mov_b32_e32 v60, v0
	v_mov_b32_e32 v61, v0
	v_mov_b32_e32 v62, v0
	v_mov_b32_e32 v63, v0
	v_mov_b32_e32 v64, v0
	v_mov_b32_e32 v65, v0
	v_mov_b32_e32 v66, v0
	v_mov_b32_e32 v67, v0
	v_mov_b32_e32 v68, v0
	v_mov_b32_e32 v69, v0
	v_mov_b32_e32 v70, v0
	v_mov_b32_e32 v71, v0
	v_mov_b32_e32 v80, v0
	v_mov_b32_e32 v81, v0
	v_mov_b32_e32 v82, v0
	v_mov_b32_e32 v83, v0
	v_mov_b32_e32 v84, v0
	v_mov_b32_e32 v85, v0
	v_mov_b32_e32 v86, v0
	v_mov_b32_e32 v87, v0
	v_mov_b32_e32 v96, v0
	v_mov_b32_e32 v97, v0
	v_mov_b32_e32 v98, v0
	v_mov_b32_e32 v99, v0
	v_mov_b32_e32 v100, v0
	v_mov_b32_e32 v101, v0
	v_mov_b32_e32 v102, v0
	v_mov_b32_e32 v103, v0
	v_mov_b32_e32 v112, v0
	v_mov_b32_e32 v113, v0
	v_mov_b32_e32 v114, v0
	v_mov_b32_e32 v115, v0
	v_mov_b32_e32 v116, v0
	v_mov_b32_e32 v117, v0
	v_mov_b32_e32 v118, v0
	v_mov_b32_e32 v119, v0
	v_mov_b32_e32 v72, v0
	v_mov_b32_e32 v73, v0
	v_mov_b32_e32 v74, v0
	v_mov_b32_e32 v75, v0
	v_mov_b32_e32 v76, v0
	v_mov_b32_e32 v77, v0
	v_mov_b32_e32 v78, v0
	v_mov_b32_e32 v79, v0
	v_mov_b32_e32 v88, v0
	v_mov_b32_e32 v89, v0
	v_mov_b32_e32 v90, v0
	v_mov_b32_e32 v91, v0
	v_mov_b32_e32 v92, v0
	v_mov_b32_e32 v93, v0
	v_mov_b32_e32 v94, v0
	v_mov_b32_e32 v95, v0
	v_mov_b32_e32 v104, v0
	v_mov_b32_e32 v105, v0
	v_mov_b32_e32 v106, v0
	v_mov_b32_e32 v107, v0
	v_mov_b32_e32 v108, v0
	v_mov_b32_e32 v109, v0
	v_mov_b32_e32 v110, v0
	v_mov_b32_e32 v111, v0
	v_mov_b32_e32 v120, v0
	v_mov_b32_e32 v121, v0
	v_mov_b32_e32 v122, v0
	v_mov_b32_e32 v123, v0
	v_mov_b32_e32 v124, v0
	v_mov_b32_e32 v125, v0
	v_mov_b32_e32 v126, v0
	v_mov_b32_e32 v127, v0
	.p2align 3

; template <class Epi>
; DI void gemm_phase(PG8_LAS unsigned char* lds, const Gemm g, const StaticOrder& S, const Epi& E, const int wv) {
;     ...
;     const bool has_next = S.next(ui + 1, nxt);
;     const char* nA = has_next ? (const char*)g.A + (size_t)nxt.pm * tstep : cA; const char* nB = has_next ? (const char*)g.Bt + (size_t)nxt.pn * tstep : cB;
;     ...
; #pragma unroll
;     for (int a = 0; a < 2; ++a)
; #pragma unroll
;       for (int b = 0; b < 2; ++b)
; #pragma unroll
;         for (int m = 0; m < 4; ++m)
; #pragma unroll
;           for (int n = 0; n < 2; ++n) acc[a][b][m][n] = (f32x4){0.f, 0.f, 0.f, 0.f};
;     cur = nxt; cA = nA; cB = nB; ++ui;
.LBB0_1060:
	s_ashr_i32 s27, s26, 31
	s_lshl_b64 s[28:29], s[26:27], 19
	s_add_u32 s28, s42, s28
	s_addc_u32 s29, s43, s29
	s_and_b64 s[30:31], exec, s[22:23]
	s_cselect_b32 s5, s7, s29
	s_cselect_b32 s27, s6, s28
	s_ashr_i32 s25, s24, 31
	s_lshl_b64 s[30:31], s[24:25], 19
	s_add_u32 s30, s44, s30
	s_addc_u32 s31, s45, s31
	s_and_b64 s[38:39], exec, s[22:23]
	s_cselect_b32 s25, s37, s31
	s_cselect_b32 s71, s36, s30
	s_add_u32 s6, s6, 0x40080
	s_addc_u32 s7, s7, 0
	s_add_u32 s72, s36, 0x100
	v_mov_b32_e32 v0, 0
	s_addc_u32 s73, s37, 0
	s_mov_b32 s74, -2
	v_mov_b32_e32 v1, v0
	v_mov_b32_e32 v2, v0
	v_mov_b32_e32 v3, v0
	v_mov_b32_e32 v4, v0
	v_mov_b32_e32 v5, v0
	v_mov_b32_e32 v6, v0
	v_mov_b32_e32 v7, v0
	v_mov_b32_e32 v16, v0
	v_mov_b32_e32 v17, v0
	v_mov_b32_e32 v18, v0
	v_mov_b32_e32 v19, v0
	v_mov_b32_e32 v20, v0
	v_mov_b32_e32 v21, v0
	v_mov_b32_e32 v22, v0
	v_mov_b32_e32 v23, v0
	v_mov_b32_e32 v32, v0
	v_mov_b32_e32 v33, v0
	v_mov_b32_e32 v34, v0
	v_mov_b32_e32 v35, v0
	v_mov_b32_e32 v36, v0
	v_mov_b32_e32 v37, v0
	v_mov_b32_e32 v38, v0
	v_mov_b32_e32 v39, v0
	v_mov_b32_e32 v48, v0
	v_mov_b32_e32 v49, v0
	v_mov_b32_e32 v50, v0
	v_mov_b32_e32 v51, v0
	v_mov_b32_e32 v52, v0
	v_mov_b32_e32 v53, v0
	v_mov_b32_e32 v54, v0
	v_mov_b32_e32 v55, v0
	v_mov_b32_e32 v8, v0
	v_mov_b32_e32 v9, v0
	v_mov_b32_e32 v10, v0
	v_mov_b32_e32 v11, v0
	v_mov_b32_e32 v12, v0
	v_mov_b32_e32 v13, v0
	v_mov_b32_e32 v14, v0
	v_mov_b32_e32 v15, v0
	v_mov_b32_e32 v24, v0
	v_mov_b32_e32 v25, v0
	v_mov_b32_e32 v26, v0
	v_mov_b32_e32 v27, v0
	v_mov_b32_e32 v28, v0
	v_mov_b32_e32 v29, v0
	v_mov_b32_e32 v30, v0
	v_mov_b32_e32 v31, v0
	v_mov_b32_e32 v40, v0
	v_mov_b32_e32 v41, v0
	v_mov_b32_e32 v42, v0
	v_mov_b32_e32 v43, v0
	v_mov_b32_e32 v44, v0
	v_mov_b32_e32 v45, v0
	v_mov_b32_e32 v46, v0
	v_mov_b32_e32 v47, v0
	v_mov_b32_e32 v56, v0
	v_mov_b32_e32 v57, v0
	v_mov_b32_e32 v58, v0
	v_mov_b32_e32 v59, v0
	v_mov_b32_e32 v60, v0
	v_mov_b32_e32 v61, v0
	v_mov_b32_e32 v62, v0
	v_mov_b32_e32 v63, v0
	v_mov_b32_e32 v64, v0
	v_mov_b32_e32 v65, v0
	v_mov_b32_e32 v66, v0
	v_mov_b32_e32 v67, v0
	v_mov_b32_e32 v68, v0
	v_mov_b32_e32 v69, v0
	v_mov_b32_e32 v70, v0
	v_mov_b32_e32 v71, v0
	v_mov_b32_e32 v80, v0
	v_mov_b32_e32 v81, v0
	v_mov_b32_e32 v82, v0
	v_mov_b32_e32 v83, v0
	v_mov_b32_e32 v84, v0
	v_mov_b32_e32 v85, v0
	v_mov_b32_e32 v86, v0
	v_mov_b32_e32 v87, v0
	v_mov_b32_e32 v96, v0
	v_mov_b32_e32 v97, v0
	v_mov_b32_e32 v98, v0
	v_mov_b32_e32 v99, v0
	v_mov_b32_e32 v100, v0
	v_mov_b32_e32 v101, v0
	v_mov_b32_e32 v102, v0
	v_mov_b32_e32 v103, v0
	v_mov_b32_e32 v112, v0
	v_mov_b32_e32 v113, v0
	v_mov_b32_e32 v114, v0
	v_mov_b32_e32 v115, v0
	v_mov_b32_e32 v116, v0
	v_mov_b32_e32 v117, v0
	v_mov_b32_e32 v118, v0
	v_mov_b32_e32 v119, v0
	v_mov_b32_e32 v72, v0
	v_mov_b32_e32 v73, v0
	v_mov_b32_e32 v74, v0
	v_mov_b32_e32 v75, v0
	v_mov_b32_e32 v76, v0
	v_mov_b32_e32 v77, v0
	v_mov_b32_e32 v78, v0
	v_mov_b32_e32 v79, v0
	v_mov_b32_e32 v88, v0
	v_mov_b32_e32 v89, v0
	v_mov_b32_e32 v90, v0
	v_mov_b32_e32 v91, v0
	v_mov_b32_e32 v92, v0
	v_mov_b32_e32 v93, v0
	v_mov_b32_e32 v94, v0
	v_mov_b32_e32 v95, v0
	v_mov_b32_e32 v104, v0
	v_mov_b32_e32 v105, v0
	v_mov_b32_e32 v106, v0
	v_mov_b32_e32 v107, v0
	v_mov_b32_e32 v108, v0
	v_mov_b32_e32 v109, v0
	v_mov_b32_e32 v110, v0
	v_mov_b32_e32 v111, v0
	v_mov_b32_e32 v120, v0
	v_mov_b32_e32 v121, v0
	v_mov_b32_e32 v122, v0
	v_mov_b32_e32 v123, v0
	v_mov_b32_e32 v124, v0
	v_mov_b32_e32 v125, v0
	v_mov_b32_e32 v126, v0
	v_mov_b32_e32 v127, v0
	.p2align 3

; DI void rope_sc(float pos, int j, float& sn, float& cs) {
;   const float fr = exp2f(-(float)j * (LOG2_THETA / 32.f));
;   float tr = pos * fr * INV_2PI;
;   tr -= floorf(tr);
;   sn = __builtin_amdgcn_sinf(tr);
;   cs = __builtin_amdgcn_cosf(tr);
; }
; template <int NHQ, int NHKV>
; DI void attn_phase_l1(const u16* __restrict__ Q, const u16* __restrict__ K, const u16* __restrict__ Vt, u16* __restrict__ O, const float* __restrict__ qg, char* smem, const int wv) {
;     ...
;     const int hq = (item >> 4) % NHQ, sq = item / (16 * NHQ), q0 = NMETA + 256 * (item & 15);
;     const u16* Kb = K + (size_t)(sq * L) * LDK + (hq / (NHQ / NHKV)) * DQK;
;     const u16* Vb = Vt + (size_t)((sq * NHKV + hq / (NHQ / NHKV)) * 128) * LP;
;     const int pq = q0 + wave * 32 + r32;
;     {
;       const u16* qrow = Q + (size_t)(sq * L + pq) * 1280 + hq * DQK + hh * 8;
;       int hho = hh; asm volatile("" : "+v"(hho));
;       float ssq = 0.f;
; #pragma unroll
;       for (int i = 0; i < NS; ++i) {
;         qf[i] = *(const bf16x8*)(qrow + 16 * i);
;         float t8[8]; unpack8(__builtin_bit_cast(u32x4, qf[i]), t8);
; #pragma unroll
;         for (int e = 0; e < 8; ++e) ssq += t8[e] * t8[e];
;       }
;       ssq = xhalf_sum(ssq);
;       const float rn = rsqrtf(ssq * (1.f / DQK) + EPS) * (0.08838834764831845f * 1.4426950408889634f);
;     ...
;       const float prow = (float)((pq - NMETA) >> 6), pcol = (float)((pq - NMETA) & 63);
;       A_QROPE(0, 2, 0, prow); A_QROPE(1, 3, 1, prow);
;       A_QROPE(4, 6, 0, pcol); A_QROPE(5, 7, 1, pcol);
.LBB0_1216:
	s_ashr_i32 s18, s28, 4
	s_lshr_b32 s19, s18, 29
	s_add_i32 s19, s18, s19
	s_and_b32 s19, s19, -8
	s_sub_i32 s24, s18, s19
	s_ashr_i32 s18, s28, 31
	s_lshr_b32 s18, s18, 25
	s_add_i32 s18, s28, s18
	s_ashr_i32 s41, s18, 7
	s_lshl_b32 s18, s28, 8
	s_and_b32 s25, s18, 0xf00
	s_mul_i32 s18, s41, 0x1010
	s_ashr_i32 s19, s18, 31
	s_lshl_b64 s[20:21], s[18:19], 9
	s_bfe_i32 s19, s24, 0x80000
	s_bfe_u32 s19, s19, 0x2000d
	s_add_i32 s19, s24, s19
	s_sext_i32_i8 s19, s19
	s_lshl_b32 s19, s19, 5
	v_add_u32_e32 v2, s25, v202
	s_and_b32 s22, s19, 0xffffff80
	s_lshl_b32 s19, s41, 8
	v_add_u32_e32 v0, s18, v2
	s_add_i32 s42, s22, s19
	v_mad_i64_i32 v[0:1], s[18:19], v0, s35, v[168:169]
	s_lshl_b32 s18, s24, 7
	s_ashr_i32 s19, s18, 31
	v_lshl_add_u64 v[0:1], s[18:19], 1, v[0:1]
	v_mov_b32_e32 v3, v200
	v_lshl_add_u64 v[0:1], v[0:1], 0, v[170:171]
	global_load_dwordx4 v[68:71], v[0:1], off
	global_load_dwordx4 v[76:79], v[0:1], off offset:32
	global_load_dwordx4 v[64:67], v[0:1], off offset:64
	global_load_dwordx4 v[72:75], v[0:1], off offset:96
	global_load_dwordx4 v[84:87], v[0:1], off offset:128
	global_load_dwordx4 v[92:95], v[0:1], off offset:160
	global_load_dwordx4 v[80:83], v[0:1], off offset:192
	global_load_dwordx4 v[88:91], v[0:1], off offset:224
	v_lshlrev_b32_e32 v17, 3, v3
	v_cvt_f32_i32_e32 v1, v17
	v_add_u32_e32 v173, -16, v2
	v_ashrrev_i32_e32 v0, 6, v173
	v_cvt_f32_i32_e32 v18, v0
	v_mul_f32_e32 v0, 0xbed49a78, v1
	v_cmp_gt_f32_e32 vcc, s36, v0
	global_load_dwordx4 v[28:31], v[166:167], off
	global_load_dwordx4 v[24:27], v[166:167], off offset:16
	v_cndmask_b32_e32 v0, 0, v208, vcc
	v_fmac_f32_e32 v0, 0xbed49a78, v1
	v_exp_f32_e32 v0, v0
	v_cndmask_b32_e32 v1, 0, v209, vcc
	global_load_dwordx4 v[36:39], v[166:167], off offset:128
	global_load_dwordx4 v[32:35], v[166:167], off offset:144
	v_and_b32_e32 v16, 63, v173
	v_ldexp_f32 v19, v0, v1
	v_or_b32_e32 v1, 1, v17
	v_cvt_f32_i32_e32 v1, v1
	v_mul_f32_e32 v0, v19, v18
	v_mul_f32_e32 v2, 0.15915494, v0
	v_floor_f32_e32 v2, v2
	v_fma_f32 v0, v0, 0.15915494, -v2
	v_mul_f32_e32 v2, 0xbed49a78, v1
	v_cmp_gt_f32_e32 vcc, s36, v2
	v_sin_f32_e32 v96, v0
	v_cos_f32_e32 v98, v0
	v_cndmask_b32_e32 v2, 0, v208, vcc
	v_fmac_f32_e32 v2, 0xbed49a78, v1
	v_exp_f32_e32 v1, v2
	v_cndmask_b32_e32 v0, 0, v209, vcc
	v_cvt_f32_ubyte0_e32 v155, v16
	v_mul_f32_e32 v16, v19, v155
	v_ldexp_f32 v20, v1, v0
	v_or_b32_e32 v1, 2, v17
	v_cvt_f32_i32_e32 v1, v1
	v_mul_f32_e32 v0, v20, v18
	v_mul_f32_e32 v2, 0.15915494, v0
	v_floor_f32_e32 v2, v2
	v_fma_f32 v0, v0, 0.15915494, -v2
	v_mul_f32_e32 v2, 0xbed49a78, v1
	v_cmp_gt_f32_e32 vcc, s36, v2
	v_sin_f32_e32 v97, v0
	v_cos_f32_e32 v99, v0
	v_cndmask_b32_e32 v2, 0, v208, vcc
	v_fmac_f32_e32 v2, 0xbed49a78, v1
	v_exp_f32_e32 v1, v2
	v_cndmask_b32_e32 v0, 0, v209, vcc
	s_ashr_i32 s23, s22, 31
	s_add_u32 s24, s29, s20
	v_ldexp_f32 v21, v1, v0
	v_or_b32_e32 v1, 3, v17
	v_cvt_f32_i32_e32 v1, v1
	v_mul_f32_e32 v0, v21, v18
	v_mul_f32_e32 v2, 0.15915494, v0
	v_floor_f32_e32 v2, v2
	v_fma_f32 v0, v0, 0.15915494, -v2
	v_mul_f32_e32 v2, 0xbed49a78, v1
	v_cmp_gt_f32_e32 vcc, s36, v2
	v_sin_f32_e32 v100, v0
	v_cos_f32_e32 v102, v0
	v_cndmask_b32_e32 v2, 0, v208, vcc
	v_fmac_f32_e32 v2, 0xbed49a78, v1
	v_exp_f32_e32 v1, v2
	v_cndmask_b32_e32 v0, 0, v209, vcc
	s_addc_u32 s25, s30, s21
	s_lshl_b64 s[22:23], s[22:23], 1
	v_ldexp_f32 v22, v1, v0
	v_or_b32_e32 v1, 4, v17
	v_cvt_f32_i32_e32 v1, v1
	v_mul_f32_e32 v0, v22, v18
	v_mul_f32_e32 v2, 0.15915494, v0
	v_floor_f32_e32 v2, v2
	v_fma_f32 v0, v0, 0.15915494, -v2
	v_mul_f32_e32 v2, 0xbed49a78, v1
	v_cmp_gt_f32_e32 vcc, s36, v2
	v_sin_f32_e32 v101, v0
	v_cos_f32_e32 v103, v0
	v_cndmask_b32_e32 v2, 0, v208, vcc
	v_fmac_f32_e32 v2, 0xbed49a78, v1
	v_exp_f32_e32 v1, v2
	v_cndmask_b32_e32 v0, 0, v209, vcc
	s_waitcnt vmcnt(11)
	v_and_b32_e32 v223, 0xffff0000, v68
	v_lshlrev_b32_e32 v222, 16, v68
	v_ldexp_f32 v23, v1, v0
	v_or_b32_e32 v1, 5, v17
	v_cvt_f32_i32_e32 v1, v1
	v_mul_f32_e32 v0, v23, v18
	v_mul_f32_e32 v2, 0.15915494, v0
	v_floor_f32_e32 v2, v2
	v_fma_f32 v0, v0, 0.15915494, -v2
	v_mul_f32_e32 v2, 0xbed49a78, v1
	v_cmp_gt_f32_e32 vcc, s36, v2
	v_sin_f32_e32 v140, v0
	v_cos_f32_e32 v142, v0
	v_cndmask_b32_e32 v2, 0, v208, vcc
	v_fmac_f32_e32 v2, 0xbed49a78, v1
	v_exp_f32_e32 v1, v2
	v_cndmask_b32_e32 v0, 0, v209, vcc
	v_mul_f32_e32 v68, v223, v223
	s_waitcnt vmcnt(6)
	v_lshlrev_b32_e32 v158, 16, v95
	v_ldexp_f32 v40, v1, v0
	v_or_b32_e32 v1, 6, v17
	v_cvt_f32_i32_e32 v1, v1
	v_mul_f32_e32 v0, v40, v18
	v_mul_f32_e32 v2, 0.15915494, v0
	v_floor_f32_e32 v2, v2
	v_fma_f32 v0, v0, 0.15915494, -v2
	v_mul_f32_e32 v2, 0xbed49a78, v1
	v_cmp_gt_f32_e32 vcc, s36, v2
	v_sin_f32_e32 v141, v0
	v_cos_f32_e32 v143, v0
	v_cndmask_b32_e32 v2, 0, v208, vcc
	v_fmac_f32_e32 v2, 0xbed49a78, v1
	v_exp_f32_e32 v1, v2
	v_cndmask_b32_e32 v0, 0, v209, vcc
	v_and_b32_e32 v159, 0xffff0000, v95
	s_waitcnt vmcnt(4)
; DI void rope_sc(float pos, int j, float& sn, float& cs) {
;   const float fr = exp2f(-(float)j * (LOG2_THETA / 32.f));
;   float tr = pos * fr * INV_2PI;
;   tr -= floorf(tr);
;   sn = __builtin_amdgcn_sinf(tr);
;   cs = __builtin_amdgcn_cosf(tr);
; }
; template <int NHQ, int NHKV>
; DI void attn_phase_l1(const u16* __restrict__ Q, const u16* __restrict__ K, const u16* __restrict__ Vt, u16* __restrict__ O, const float* __restrict__ qg, char* smem, const int wv) {
;     ...
;       for (int i = 0; i < NS; ++i) {
;         qf[i] = *(const bf16x8*)(qrow + 16 * i);
;         float t8[8]; unpack8(__builtin_bit_cast(u32x4, qf[i]), t8);
; #pragma unroll
;         for (int e = 0; e < 8; ++e) ssq += t8[e] * t8[e];
;       }
;       ssq = xhalf_sum(ssq);
;       const float rn = rsqrtf(ssq * (1.f / DQK) + EPS) * (0.08838834764831845f * 1.4426950408889634f);
;     ...
;       const float prow = (float)((pq - NMETA) >> 6), pcol = (float)((pq - NMETA) & 63);
;       A_QROPE(0, 2, 0, prow); A_QROPE(1, 3, 1, prow);
;       A_QROPE(4, 6, 0, pcol); A_QROPE(5, 7, 1, pcol);
	v_lshlrev_b32_e32 v156, 16, v91
	v_ldexp_f32 v41, v1, v0
	v_or_b32_e32 v1, 7, v17
	v_cvt_f32_i32_e32 v1, v1
	v_mul_f32_e32 v0, v41, v18
	v_mul_f32_e32 v2, 0.15915494, v0
	v_floor_f32_e32 v2, v2
	v_fma_f32 v0, v0, 0.15915494, -v2
	v_mul_f32_e32 v2, 0xbed49a78, v1
	v_cmp_gt_f32_e32 vcc, s36, v2
	v_sin_f32_e32 v180, v0
	v_cos_f32_e32 v182, v0
	v_cndmask_b32_e32 v2, 0, v208, vcc
	v_fmac_f32_e32 v2, 0xbed49a78, v1
	v_exp_f32_e32 v1, v2
	v_cndmask_b32_e32 v0, 0, v209, vcc
	v_and_b32_e32 v157, 0xffff0000, v91
	v_lshlrev_b32_e32 v174, 16, v94
	v_ldexp_f32 v42, v1, v0
	v_mul_f32_e32 v0, v42, v18
	v_mul_f32_e32 v1, 0.15915494, v0
	v_floor_f32_e32 v1, v1
	v_fma_f32 v0, v0, 0.15915494, -v1
	v_add_u32_e32 v1, 16, v17
	v_cvt_f32_i32_e32 v4, v1
	v_and_b32_e32 v175, 0xffff0000, v94
	v_lshlrev_b32_e32 v94, 16, v90
	v_and_b32_e32 v95, 0xffff0000, v90
	v_mul_f32_e32 v5, 0xbed49a78, v4
	v_cmp_gt_f32_e32 vcc, s36, v5
	v_lshlrev_b32_e32 v176, 16, v93
	v_and_b32_e32 v177, 0xffff0000, v93
	v_cndmask_b32_e32 v5, 0, v208, vcc
	v_fmac_f32_e32 v5, 0xbed49a78, v4
	v_exp_f32_e32 v43, v5
	v_cndmask_b32_e32 v44, 0, v209, vcc
	v_lshlrev_b32_e32 v90, 16, v89
	v_and_b32_e32 v91, 0xffff0000, v89
	v_ldexp_f32 v124, v43, v44
	v_add_u32_e32 v44, 17, v17
	v_cvt_f32_i32_e32 v44, v44
	v_mul_f32_e32 v43, v124, v18
	v_mul_f32_e32 v45, 0.15915494, v43
	v_floor_f32_e32 v45, v45
	v_fma_f32 v43, v43, 0.15915494, -v45
	v_mul_f32_e32 v45, 0xbed49a78, v44
	v_cmp_gt_f32_e32 vcc, s36, v45
	v_sin_f32_e32 v104, v43
	v_cos_f32_e32 v106, v43
	v_cndmask_b32_e32 v45, 0, v208, vcc
	v_fmac_f32_e32 v45, 0xbed49a78, v44
	v_exp_f32_e32 v44, v45
	v_cndmask_b32_e32 v43, 0, v209, vcc
	v_lshlrev_b32_e32 v178, 16, v92
	v_and_b32_e32 v179, 0xffff0000, v92
	v_ldexp_f32 v125, v44, v43
	v_add_u32_e32 v44, 18, v17
	v_cvt_f32_i32_e32 v44, v44
	v_mul_f32_e32 v43, v125, v18
	v_mul_f32_e32 v45, 0.15915494, v43
	v_floor_f32_e32 v45, v45
	v_fma_f32 v43, v43, 0.15915494, -v45
	v_mul_f32_e32 v45, 0xbed49a78, v44
	v_cmp_gt_f32_e32 vcc, s36, v45
	v_sin_f32_e32 v105, v43
	v_cos_f32_e32 v107, v43
	v_cndmask_b32_e32 v45, 0, v208, vcc
	v_fmac_f32_e32 v45, 0xbed49a78, v44
	v_exp_f32_e32 v44, v45
	v_cndmask_b32_e32 v43, 0, v209, vcc
	v_lshlrev_b32_e32 v92, 16, v88
	v_and_b32_e32 v93, 0xffff0000, v88
	v_ldexp_f32 v144, v44, v43
	v_add_u32_e32 v44, 19, v17
	v_cvt_f32_i32_e32 v44, v44
	v_mul_f32_e32 v43, v144, v18
	v_mul_f32_e32 v45, 0.15915494, v43
	v_floor_f32_e32 v45, v45
	v_fma_f32 v43, v43, 0.15915494, -v45
	v_mul_f32_e32 v45, 0xbed49a78, v44
	v_cmp_gt_f32_e32 vcc, s36, v45
	v_sin_f32_e32 v108, v43
	v_cos_f32_e32 v110, v43
	v_cndmask_b32_e32 v45, 0, v208, vcc
	v_fmac_f32_e32 v45, 0xbed49a78, v44
	v_exp_f32_e32 v44, v45
	v_cndmask_b32_e32 v43, 0, v209, vcc
	v_lshlrev_b32_e32 v184, 16, v87
	v_and_b32_e32 v185, 0xffff0000, v87
	v_ldexp_f32 v145, v44, v43
	v_add_u32_e32 v44, 20, v17
	v_cvt_f32_i32_e32 v44, v44
	v_mul_f32_e32 v43, v145, v18
	v_mul_f32_e32 v45, 0.15915494, v43
	v_floor_f32_e32 v45, v45
	v_fma_f32 v43, v43, 0.15915494, -v45
	v_mul_f32_e32 v45, 0xbed49a78, v44
	v_cmp_gt_f32_e32 vcc, s36, v45
	v_sin_f32_e32 v109, v43
	v_cos_f32_e32 v111, v43
	v_cndmask_b32_e32 v45, 0, v208, vcc
	v_fmac_f32_e32 v45, 0xbed49a78, v44
	v_exp_f32_e32 v44, v45
	v_cndmask_b32_e32 v43, 0, v209, vcc
	v_lshlrev_b32_e32 v88, 16, v83
	v_and_b32_e32 v89, 0xffff0000, v83
	v_ldexp_f32 v148, v44, v43
	v_add_u32_e32 v44, 21, v17
	v_lshlrev_b32_e32 v186, 16, v86
	v_and_b32_e32 v187, 0xffff0000, v86
	v_lshlrev_b32_e32 v86, 16, v82
	v_and_b32_e32 v87, 0xffff0000, v82
	v_lshlrev_b32_e32 v188, 16, v85
	v_and_b32_e32 v189, 0xffff0000, v85
	v_lshlrev_b32_e32 v82, 16, v81
	v_and_b32_e32 v83, 0xffff0000, v81
	v_lshlrev_b32_e32 v190, 16, v84
	v_and_b32_e32 v191, 0xffff0000, v84
	v_lshlrev_b32_e32 v84, 16, v80
	v_and_b32_e32 v85, 0xffff0000, v80
	v_lshlrev_b32_e32 v192, 16, v79
	v_and_b32_e32 v193, 0xffff0000, v79
	v_lshlrev_b32_e32 v80, 16, v75
	v_and_b32_e32 v81, 0xffff0000, v75
	v_lshlrev_b32_e32 v194, 16, v78
	v_and_b32_e32 v195, 0xffff0000, v78
	v_lshlrev_b32_e32 v78, 16, v74
	v_and_b32_e32 v79, 0xffff0000, v74
	v_lshlrev_b32_e32 v196, 16, v77
	v_and_b32_e32 v197, 0xffff0000, v77
	v_lshlrev_b32_e32 v74, 16, v73
	v_and_b32_e32 v75, 0xffff0000, v73
	v_lshlrev_b32_e32 v198, 16, v76
	v_and_b32_e32 v199, 0xffff0000, v76
	v_lshlrev_b32_e32 v76, 16, v72
	v_and_b32_e32 v77, 0xffff0000, v72
	v_lshlrev_b32_e32 v72, 16, v71
	v_and_b32_e32 v73, 0xffff0000, v71
	v_lshlrev_b32_e32 v214, 16, v67
	v_and_b32_e32 v215, 0xffff0000, v67
	v_lshlrev_b32_e32 v216, 16, v70
	v_and_b32_e32 v217, 0xffff0000, v70
	v_lshlrev_b32_e32 v70, 16, v66
	v_and_b32_e32 v71, 0xffff0000, v66
	v_lshlrev_b32_e32 v66, 16, v69
	v_and_b32_e32 v67, 0xffff0000, v69
	v_pk_fma_f32 v[68:69], v[222:223], v[222:223], v[68:69] op_sel_hi:[1,1,0]
	v_cvt_f32_i32_e32 v44, v44
	v_lshlrev_b32_e32 v220, 16, v65
	v_and_b32_e32 v221, 0xffff0000, v65
	v_lshlrev_b32_e32 v224, 16, v64
	v_and_b32_e32 v225, 0xffff0000, v64
	v_pk_fma_f32 v[64:65], v[66:67], v[66:67], v[68:69]
	v_mul_f32_e32 v68, v67, v67
	v_mul_f32_e32 v43, v148, v18
	v_pk_add_f32 v[64:65], v[68:69], v[64:65] op_sel_hi:[0,1]
	v_mul_f32_e32 v45, 0.15915494, v43
	v_pk_fma_f32 v[64:65], v[216:217], v[216:217], v[64:65]
	v_mul_f32_e32 v68, v217, v217
	v_floor_f32_e32 v45, v45
	v_pk_add_f32 v[64:65], v[68:69], v[64:65] op_sel_hi:[0,1]
	v_fma_f32 v43, v43, 0.15915494, -v45
	v_mul_f32_e32 v45, 0xbed49a78, v44
	v_pk_fma_f32 v[64:65], v[72:73], v[72:73], v[64:65]
	v_mul_f32_e32 v68, v73, v73
	v_cmp_gt_f32_e32 vcc, s36, v45
	v_pk_add_f32 v[64:65], v[68:69], v[64:65] op_sel_hi:[0,1]
	v_pk_fma_f32 v[64:65], v[198:199], v[198:199], v[64:65]
	v_cndmask_b32_e32 v45, 0, v208, vcc
; DI void rope_sc(float pos, int j, float& sn, float& cs) {
;   const float fr = exp2f(-(float)j * (LOG2_THETA / 32.f));
;   float tr = pos * fr * INV_2PI;
;   tr -= floorf(tr);
;   sn = __builtin_amdgcn_sinf(tr);
;   cs = __builtin_amdgcn_cosf(tr);
; }
; template <int NHQ, int NHKV>
; DI void attn_phase_l1(const u16* __restrict__ Q, const u16* __restrict__ K, const u16* __restrict__ Vt, u16* __restrict__ O, const float* __restrict__ qg, char* smem, const int wv) {
;     ...
;       for (int i = 0; i < NS; ++i) {
;         qf[i] = *(const bf16x8*)(qrow + 16 * i);
;         float t8[8]; unpack8(__builtin_bit_cast(u32x4, qf[i]), t8);
; #pragma unroll
;         for (int e = 0; e < 8; ++e) ssq += t8[e] * t8[e];
;       }
;       ssq = xhalf_sum(ssq);
;       const float rn = rsqrtf(ssq * (1.f / DQK) + EPS) * (0.08838834764831845f * 1.4426950408889634f);
;     ...
;       const float prow = (float)((pq - NMETA) >> 6), pcol = (float)((pq - NMETA) & 63);
;       A_QROPE(0, 2, 0, prow); A_QROPE(1, 3, 1, prow);
;       A_QROPE(4, 6, 0, pcol); A_QROPE(5, 7, 1, pcol);
	v_mul_f32_e32 v68, v199, v199
	v_fmac_f32_e32 v45, 0xbed49a78, v44
	v_pk_add_f32 v[64:65], v[68:69], v[64:65] op_sel_hi:[0,1]
	v_exp_f32_e32 v44, v45
	v_pk_fma_f32 v[64:65], v[196:197], v[196:197], v[64:65]
	v_mul_f32_e32 v68, v197, v197
	v_pk_add_f32 v[64:65], v[68:69], v[64:65] op_sel_hi:[0,1]
	v_pk_fma_f32 v[64:65], v[194:195], v[194:195], v[64:65]
	v_mul_f32_e32 v68, v195, v195
	v_sin_f32_e32 v112, v43
	v_cos_f32_e32 v114, v43
	v_cndmask_b32_e32 v43, 0, v209, vcc
	v_pk_add_f32 v[64:65], v[68:69], v[64:65] op_sel_hi:[0,1]
	v_ldexp_f32 v149, v44, v43
	v_add_u32_e32 v44, 22, v17
	v_pk_fma_f32 v[64:65], v[192:193], v[192:193], v[64:65]
	v_mul_f32_e32 v68, v193, v193
	v_cvt_f32_i32_e32 v44, v44
	v_pk_add_f32 v[64:65], v[68:69], v[64:65] op_sel_hi:[0,1]
	v_mul_f32_e32 v43, v149, v18
	v_pk_fma_f32 v[64:65], v[224:225], v[224:225], v[64:65]
	v_mul_f32_e32 v68, v225, v225
	v_mul_f32_e32 v45, 0.15915494, v43
	v_pk_add_f32 v[64:65], v[68:69], v[64:65] op_sel_hi:[0,1]
	v_floor_f32_e32 v45, v45
	v_pk_fma_f32 v[64:65], v[220:221], v[220:221], v[64:65]
	v_mul_f32_e32 v68, v221, v221
	v_fma_f32 v43, v43, 0.15915494, -v45
	v_mul_f32_e32 v45, 0xbed49a78, v44
	v_pk_add_f32 v[64:65], v[68:69], v[64:65] op_sel_hi:[0,1]
	v_cmp_gt_f32_e32 vcc, s36, v45
	v_pk_fma_f32 v[64:65], v[70:71], v[70:71], v[64:65]
	v_mul_f32_e32 v68, v71, v71
	v_cndmask_b32_e32 v45, 0, v208, vcc
	v_pk_add_f32 v[64:65], v[68:69], v[64:65] op_sel_hi:[0,1]
	v_fmac_f32_e32 v45, 0xbed49a78, v44
	v_pk_fma_f32 v[64:65], v[214:215], v[214:215], v[64:65]
	v_mul_f32_e32 v68, v215, v215
	v_exp_f32_e32 v44, v45
	v_pk_add_f32 v[64:65], v[68:69], v[64:65] op_sel_hi:[0,1]
	v_pk_fma_f32 v[64:65], v[76:77], v[76:77], v[64:65]
	v_mul_f32_e32 v68, v77, v77
	v_pk_add_f32 v[64:65], v[68:69], v[64:65] op_sel_hi:[0,1]
	v_sin_f32_e32 v113, v43
	v_cos_f32_e32 v115, v43
	v_cndmask_b32_e32 v43, 0, v209, vcc
	v_add_u32_e32 v17, 23, v17
	v_pk_fma_f32 v[64:65], v[74:75], v[74:75], v[64:65]
	v_mul_f32_e32 v68, v75, v75
	v_ldexp_f32 v152, v44, v43
	v_cvt_f32_i32_e32 v17, v17
	v_pk_add_f32 v[64:65], v[68:69], v[64:65] op_sel_hi:[0,1]
	v_mul_f32_e32 v43, v152, v18
	v_pk_fma_f32 v[64:65], v[78:79], v[78:79], v[64:65]
	v_mul_f32_e32 v68, v79, v79
	v_mul_f32_e32 v44, 0.15915494, v43
	v_pk_add_f32 v[64:65], v[68:69], v[64:65] op_sel_hi:[0,1]
	v_floor_f32_e32 v44, v44
	v_pk_fma_f32 v[64:65], v[80:81], v[80:81], v[64:65]
	v_mul_f32_e32 v68, v81, v81
	v_fma_f32 v43, v43, 0.15915494, -v44
	v_mul_f32_e32 v44, 0xbed49a78, v17
	v_pk_add_f32 v[64:65], v[68:69], v[64:65] op_sel_hi:[0,1]
	v_cmp_gt_f32_e32 vcc, s36, v44
	v_pk_fma_f32 v[64:65], v[190:191], v[190:191], v[64:65]
	v_mul_f32_e32 v68, v191, v191
	v_cndmask_b32_e32 v44, 0, v208, vcc
	v_pk_add_f32 v[64:65], v[68:69], v[64:65] op_sel_hi:[0,1]
	v_fmac_f32_e32 v44, 0xbed49a78, v17
	v_pk_fma_f32 v[64:65], v[188:189], v[188:189], v[64:65]
	v_mul_f32_e32 v68, v189, v189
	v_exp_f32_e32 v17, v44
	v_pk_add_f32 v[64:65], v[68:69], v[64:65] op_sel_hi:[0,1]
	v_pk_fma_f32 v[64:65], v[186:187], v[186:187], v[64:65]
	v_mul_f32_e32 v68, v187, v187
	v_pk_add_f32 v[64:65], v[68:69], v[64:65] op_sel_hi:[0,1]
	v_sin_f32_e32 v132, v43
	v_cos_f32_e32 v134, v43
	v_cndmask_b32_e32 v43, 0, v209, vcc
	v_pk_fma_f32 v[64:65], v[184:185], v[184:185], v[64:65]
	v_mul_f32_e32 v68, v185, v185
	v_ldexp_f32 v153, v17, v43
	v_pk_add_f32 v[64:65], v[68:69], v[64:65] op_sel_hi:[0,1]
	v_mul_f32_e32 v17, v153, v18
	v_pk_fma_f32 v[64:65], v[178:179], v[178:179], v[64:65]
	v_mul_f32_e32 v68, v179, v179
	v_mul_f32_e32 v18, 0.15915494, v17
	v_pk_add_f32 v[64:65], v[68:69], v[64:65] op_sel_hi:[0,1]
	v_floor_f32_e32 v18, v18
	v_pk_fma_f32 v[64:65], v[176:177], v[176:177], v[64:65]
	v_mul_f32_e32 v68, v177, v177
	v_fma_f32 v17, v17, 0.15915494, -v18
	v_pk_add_f32 v[64:65], v[68:69], v[64:65] op_sel_hi:[0,1]
	v_sin_f32_e32 v133, v17
	v_cos_f32_e32 v135, v17
	v_mul_f32_e32 v17, 0.15915494, v16
	v_pk_fma_f32 v[64:65], v[174:175], v[174:175], v[64:65]
	v_mul_f32_e32 v68, v175, v175
	v_floor_f32_e32 v17, v17
	v_pk_add_f32 v[64:65], v[68:69], v[64:65] op_sel_hi:[0,1]
	v_fma_f32 v16, v16, 0.15915494, -v17
	v_pk_fma_f32 v[64:65], v[158:159], v[158:159], v[64:65]
	v_mul_f32_e32 v68, v159, v159
	v_sin_f32_e32 v120, v16
	v_cos_f32_e32 v122, v16
	v_mul_f32_e32 v16, v20, v155
	v_pk_add_f32 v[64:65], v[68:69], v[64:65] op_sel_hi:[0,1]
	v_mul_f32_e32 v17, 0.15915494, v16
	v_pk_fma_f32 v[64:65], v[84:85], v[84:85], v[64:65]
	v_mul_f32_e32 v68, v85, v85
	v_floor_f32_e32 v17, v17
	v_pk_add_f32 v[64:65], v[68:69], v[64:65] op_sel_hi:[0,1]
	v_fma_f32 v16, v16, 0.15915494, -v17
	v_pk_fma_f32 v[64:65], v[82:83], v[82:83], v[64:65]
	v_mul_f32_e32 v68, v83, v83
	v_sin_f32_e32 v121, v16
	v_cos_f32_e32 v123, v16
	v_mul_f32_e32 v16, v21, v155
	v_pk_add_f32 v[64:65], v[68:69], v[64:65] op_sel_hi:[0,1]
	v_mul_f32_e32 v17, 0.15915494, v16
	v_pk_fma_f32 v[64:65], v[86:87], v[86:87], v[64:65]
	v_mul_f32_e32 v68, v87, v87
	v_floor_f32_e32 v17, v17
	v_pk_add_f32 v[64:65], v[68:69], v[64:65] op_sel_hi:[0,1]
	v_fma_f32 v16, v16, 0.15915494, -v17
	v_pk_fma_f32 v[64:65], v[88:89], v[88:89], v[64:65]
	v_mul_f32_e32 v68, v89, v89
	v_sin_f32_e32 v128, v16
	v_cos_f32_e32 v130, v16
	v_mul_f32_e32 v16, v22, v155
	v_pk_add_f32 v[64:65], v[68:69], v[64:65] op_sel_hi:[0,1]
	v_mul_f32_e32 v17, 0.15915494, v16
	v_pk_fma_f32 v[64:65], v[92:93], v[92:93], v[64:65]
	v_mul_f32_e32 v68, v93, v93
	v_floor_f32_e32 v17, v17
	v_pk_add_f32 v[64:65], v[68:69], v[64:65] op_sel_hi:[0,1]
	v_fma_f32 v16, v16, 0.15915494, -v17
	v_pk_fma_f32 v[64:65], v[90:91], v[90:91], v[64:65]
	v_mul_f32_e32 v68, v91, v91
	v_sin_f32_e32 v129, v16
	v_cos_f32_e32 v131, v16
	v_mul_f32_e32 v16, v23, v155
; #define B_LOADK(Kb_, tile_) do { const char* kp_ = (const char*)(Kb_) + (size_t)(tile_) * (64 * LDK * 2); const unsigned ko_ = ((tile_) == NT - 1) ? koffL : koff; \
;     _Pragma("unroll") for (int i_ = 0; i_ < NKC; ++i_) rk[i_] = *(const u32x4*)(kp_ + ko_ + i_ * 128); } while (0)
; #define B_LOADV(Vb_, tile_) do { const char* vp_ = (const char*)(Vb_) + (size_t)(tile_) * 128; \
;     rv[0] = *(const u32x4*)(vp_ + voff); rv[1] = *(const u32x4*)(vp_ + voff + 64 * LP * 2); } while (0)
; #define B_WRITEK(bi_) do { char* b_w = kb0 + (bi_) * KBYTES + kwoff; \
;     _Pragma("unroll") for (int i_ = 0; i_ < NKC; ++i_) *(u32x4*)(b_w + i_ * 128) = rk[i_]; } while (0)
; #define B_WRITEV(bi_) do { char* b_w = vb0 + (bi_) * VBYTES + vwoff; \
;     *(u32x4*)(b_w) = rv[0]; *(u32x4*)(b_w + 64 * VSTR) = rv[1]; } while (0)
; template <int NHQ, int NHKV>
; DI void attn_phase_l1(const u16* __restrict__ Q, const u16* __restrict__ K, const u16* __restrict__ Vt, u16* __restrict__ O, const float* __restrict__ qg, char* smem, const int wv) {
;     ...
;       ssq = xhalf_sum(ssq);
;       const float rn = rsqrtf(ssq * (1.f / DQK) + EPS) * (0.08838834764831845f * 1.4426950408889634f);
;     ...
;       const float prow = (float)((pq - NMETA) >> 6), pcol = (float)((pq - NMETA) & 63);
;       A_QROPE(0, 2, 0, prow); A_QROPE(1, 3, 1, prow);
;       A_QROPE(4, 6, 0, pcol); A_QROPE(5, 7, 1, pcol);
;     ...
;     }
;     float l = 0.f;
; #pragma unroll
;     for (int d = 0; d < 4; ++d)
; #pragma unroll
;       for (int i = 0; i < 16; ++i) o[d][i] = 0.f;
;     __syncthreads();
;     B_LOADK(Kb, 0); B_WRITEK(0); B_LOADK(Kb, 1); B_WRITEK(1); B_LOADV(Vb, 0); B_WRITEV(0);
;     B_LOADK(Kb, 2); B_LOADV(Vb, 1);
	v_pk_add_f32 v[64:65], v[68:69], v[64:65] op_sel_hi:[0,1]
	v_mul_f32_e32 v17, 0.15915494, v16
	v_pk_fma_f32 v[64:65], v[94:95], v[94:95], v[64:65]
	v_mul_f32_e32 v68, v95, v95
	v_floor_f32_e32 v17, v17
	v_pk_add_f32 v[64:65], v[68:69], v[64:65] op_sel_hi:[0,1]
	v_fma_f32 v16, v16, 0.15915494, -v17
	v_pk_fma_f32 v[64:65], v[156:157], v[156:157], v[64:65]
	v_mul_f32_e32 v68, v157, v157
	v_sin_f32_e32 v136, v16
	v_cos_f32_e32 v138, v16
	v_mul_f32_e32 v16, v40, v155
	v_pk_add_f32 v[64:65], v[68:69], v[64:65] op_sel_hi:[0,1]
	v_mul_f32_e32 v17, 0.15915494, v16
	v_mov_b32_e32 v65, v64
	v_floor_f32_e32 v17, v17
	s_nop 0
	v_permlane32_swap_b32_e32 v64, v65
	v_fma_f32 v16, v16, 0.15915494, -v17
	v_add_f32_e32 v64, v64, v65
	v_sin_f32_e32 v137, v16
	v_cos_f32_e32 v139, v16
	v_mul_f32_e32 v16, v41, v155
	v_fmamk_f32 v64, v64, 0x3c000000, v210
	v_mul_f32_e32 v17, 0.15915494, v16
	v_mul_f32_e32 v65, 0x4b800000, v64
	v_cmp_gt_f32_e32 vcc, s37, v64
	v_floor_f32_e32 v17, v17
	v_fma_f32 v16, v16, 0.15915494, -v17
	v_cndmask_b32_e32 v64, v64, v65, vcc
	v_mul_f32_e32 v153, v153, v155
	v_rsq_f32_e32 v64, v64
	v_sin_f32_e32 v116, v16
	v_cos_f32_e32 v118, v16
	v_mul_f32_e32 v16, v42, v155
	v_mul_f32_e32 v124, v124, v155
	v_mul_f32_e32 v125, v125, v155
	v_mul_f32_e32 v144, v144, v155
	v_mul_f32_e32 v145, v145, v155
	v_mul_f32_e32 v148, v148, v155
	v_mul_f32_e32 v149, v149, v155
	v_mul_f32_e32 v152, v152, v155
	v_mul_f32_e32 v155, 0.15915494, v153
	v_floor_f32_e32 v155, v155
	v_fma_f32 v65, v153, 0.15915494, -v155
	v_sin_f32_e32 v153, v65
	v_cos_f32_e32 v155, v65
	v_mul_f32_e32 v65, 0x45800000, v64
	v_cndmask_b32_e32 v64, v64, v65, vcc
	v_sin_f32_e32 v181, v0
	v_cos_f32_e32 v183, v0
	global_load_dwordx4 v[8:11], v[166:167], off offset:64
	global_load_dwordx4 v[0:3], v[166:167], off offset:80
	v_mul_f32_e32 v64, 0x3e0293ee, v64
	global_load_dwordx4 v[12:15], v[166:167], off offset:192
	global_load_dwordx4 v[4:7], v[166:167], off offset:208
	s_waitcnt vmcnt(7)
	v_pk_mul_f32 v[28:29], v[28:29], v[64:65] op_sel_hi:[1,0]
	v_pk_mul_f32 v[30:31], v[30:31], v[64:65] op_sel_hi:[1,0]
	v_pk_mul_f32 v[28:29], v[28:29], v[222:223]
	s_waitcnt vmcnt(5)
	v_pk_mul_f32 v[36:37], v[36:37], v[64:65] op_sel_hi:[1,0]
	v_pk_mul_f32 v[30:31], v[30:31], v[66:67]
	v_pk_mul_f32 v[36:37], v[36:37], v[224:225]
	v_pk_mul_f32 v[66:67], v[96:97], v[28:29]
	v_pk_mul_f32 v[38:39], v[38:39], v[64:65] op_sel_hi:[1,0]
	v_pk_fma_f32 v[66:67], v[98:99], v[36:37], v[66:67]
	v_pk_mul_f32 v[36:37], v[96:97], v[36:37]
	v_pk_mul_f32 v[24:25], v[24:25], v[64:65] op_sel_hi:[1,0]
	v_pk_mul_f32 v[38:39], v[38:39], v[220:221]
	v_pk_fma_f32 v[28:29], v[98:99], v[28:29], v[36:37] neg_lo:[0,0,1] neg_hi:[0,0,1]
	v_pk_mul_f32 v[36:37], v[100:101], v[30:31]
	v_pk_mul_f32 v[24:25], v[24:25], v[216:217]
	s_waitcnt vmcnt(4)
	v_pk_mul_f32 v[32:33], v[32:33], v[64:65] op_sel_hi:[1,0]
	v_pk_fma_f32 v[36:37], v[102:103], v[38:39], v[36:37]
	v_pk_mul_f32 v[38:39], v[100:101], v[38:39]
	v_pk_mul_f32 v[26:27], v[26:27], v[64:65] op_sel_hi:[1,0]
	v_pk_mul_f32 v[32:33], v[32:33], v[70:71]
	v_pk_fma_f32 v[30:31], v[102:103], v[30:31], v[38:39] neg_lo:[0,0,1] neg_hi:[0,0,1]
	v_pk_mul_f32 v[38:39], v[140:141], v[24:25]
	s_add_u32 s24, s24, s22
	global_load_dwordx4 v[60:63], v[166:167], off offset:256
	global_load_dwordx4 v[56:59], v[166:167], off offset:272
	global_load_dwordx4 v[52:55], v[166:167], off offset:384
	global_load_dwordx4 v[48:51], v[166:167], off offset:400
	v_pk_mul_f32 v[26:27], v[26:27], v[72:73]
	v_pk_mul_f32 v[34:35], v[34:35], v[64:65] op_sel_hi:[1,0]
	v_pk_fma_f32 v[98:99], v[142:143], v[32:33], v[38:39]
	v_pk_mul_f32 v[32:33], v[140:141], v[32:33]
	s_mul_i32 s26, s42, 0x2080
	s_addc_u32 s25, s25, s23
	v_pk_mul_f32 v[34:35], v[34:35], v[214:215]
	v_pk_fma_f32 v[24:25], v[142:143], v[24:25], v[32:33] neg_lo:[0,0,1] neg_hi:[0,0,1]
	v_pk_mul_f32 v[32:33], v[180:181], v[26:27]
	s_mul_hi_i32 s27, s42, 0x2080
	s_add_u32 s26, s31, s26
	v_pk_fma_f32 v[140:141], v[182:183], v[34:35], v[32:33]
	v_pk_mul_f32 v[32:33], v[180:181], v[34:35]
	v_lshl_add_u64 v[180:181], s[24:25], 0, v[160:161]
	s_addc_u32 s27, s34, s27
	v_pk_fma_f32 v[26:27], v[182:183], v[26:27], v[32:33] neg_lo:[0,0,1] neg_hi:[0,0,1]
	v_add_co_u32_e32 v32, vcc, s38, v180
	v_mul_f32_e32 v17, 0.15915494, v16
	s_nop 0
	v_addc_co_u32_e32 v33, vcc, 0, v181, vcc
	v_lshl_add_u64 v[142:143], s[26:27], 0, v[162:163]
	v_floor_f32_e32 v17, v17
	v_add_co_u32_e32 v182, vcc, s39, v142
	v_fma_f32 v16, v16, 0.15915494, -v17
	v_cvt_pk_bf16_f32 v97, v36, v37
	v_lshl_add_u64 v[36:37], v[180:181], 0, s[8:9]
	v_addc_co_u32_e32 v183, vcc, 0, v143, vcc
	v_sin_f32_e32 v117, v16
	v_cos_f32_e32 v119, v16
	global_load_dwordx4 v[44:47], v[166:167], off offset:320
	global_load_dwordx4 v[40:43], v[166:167], off offset:336
	global_load_dwordx4 v[20:23], v[166:167], off offset:448
	global_load_dwordx4 v[16:19], v[166:167], off offset:464
	v_cvt_pk_bf16_f32 v100, v28, v29
	v_cvt_pk_bf16_f32 v101, v30, v31
	v_cvt_pk_bf16_f32 v102, v24, v25
	v_cvt_pk_bf16_f32 v103, v26, v27
	v_cvt_pk_bf16_f32 v96, v66, v67
	s_barrier
; #define B_LOADK(Kb_, tile_) do { const char* kp_ = (const char*)(Kb_) + (size_t)(tile_) * (64 * LDK * 2); const unsigned ko_ = ((tile_) == NT - 1) ? koffL : koff; \
;     _Pragma("unroll") for (int i_ = 0; i_ < NKC; ++i_) rk[i_] = *(const u32x4*)(kp_ + ko_ + i_ * 128); } while (0)
; #define B_LOADV(Vb_, tile_) do { const char* vp_ = (const char*)(Vb_) + (size_t)(tile_) * 128; \
;     rv[0] = *(const u32x4*)(vp_ + voff); rv[1] = *(const u32x4*)(vp_ + voff + 64 * LP * 2); } while (0)
; #define B_WRITEK(bi_) do { char* b_w = kb0 + (bi_) * KBYTES + kwoff; \
;     _Pragma("unroll") for (int i_ = 0; i_ < NKC; ++i_) *(u32x4*)(b_w + i_ * 128) = rk[i_]; } while (0)
; #define B_WRITEV(bi_) do { char* b_w = vb0 + (bi_) * VBYTES + vwoff; \
;     *(u32x4*)(b_w) = rv[0]; *(u32x4*)(b_w + 64 * VSTR) = rv[1]; } while (0)
; template <int NHQ, int NHKV>
; DI void attn_phase_l1(const u16* __restrict__ Q, const u16* __restrict__ K, const u16* __restrict__ Vt, u16* __restrict__ O, const float* __restrict__ qg, char* smem, const int wv) {
;     ...
;       const float prow = (float)((pq - NMETA) >> 6), pcol = (float)((pq - NMETA) & 63);
;       A_QROPE(0, 2, 0, prow); A_QROPE(1, 3, 1, prow);
;       A_QROPE(4, 6, 0, pcol); A_QROPE(5, 7, 1, pcol);
;     ...
;     B_LOADK(Kb, 0); B_WRITEK(0); B_LOADK(Kb, 1); B_WRITEK(1); B_LOADV(Vb, 0); B_WRITEV(0);
;     B_LOADK(Kb, 2); B_LOADV(Vb, 1);
;     __syncthreads();
	global_load_dwordx4 v[24:27], v[180:181], off
	global_load_dwordx4 v[28:31], v[180:181], off offset:128
	s_nop 0
	global_load_dwordx4 v[32:35], v[32:33], off
	s_nop 0
	global_load_dwordx4 v[36:39], v[36:37], off offset:128
	v_cvt_pk_bf16_f32 v98, v98, v99
	global_load_dwordx4 v[66:69], v[142:143], off
	global_load_dwordx4 v[70:73], v[182:183], off
	s_waitcnt vmcnt(5)
	ds_write_b128 v203, v[24:27]
	s_waitcnt vmcnt(4)
	ds_write_b128 v203, v[28:31] offset:128
	s_waitcnt vmcnt(3)
	ds_write_b128 v203, v[32:35] offset:17408
	s_waitcnt vmcnt(2)
	ds_write_b128 v203, v[36:39] offset:17536
	v_pk_mul_f32 v[8:9], v[8:9], v[64:65] op_sel_hi:[1,0]
	v_pk_mul_f32 v[12:13], v[12:13], v[64:65] op_sel_hi:[1,0]
	v_pk_mul_f32 v[8:9], v[8:9], v[198:199]
	v_pk_mul_f32 v[14:15], v[14:15], v[64:65] op_sel_hi:[1,0]
	v_pk_mul_f32 v[10:11], v[10:11], v[64:65] op_sel_hi:[1,0]
	v_pk_mul_f32 v[12:13], v[12:13], v[76:77]
	v_pk_mul_f32 v[14:15], v[14:15], v[74:75]
	v_pk_mul_f32 v[74:75], v[104:105], v[8:9]
	v_pk_mul_f32 v[10:11], v[10:11], v[196:197]
	v_pk_fma_f32 v[74:75], v[106:107], v[12:13], v[74:75]
	v_pk_mul_f32 v[12:13], v[104:105], v[12:13]
	v_pk_mul_f32 v[0:1], v[0:1], v[64:65] op_sel_hi:[1,0]
	v_pk_fma_f32 v[8:9], v[106:107], v[8:9], v[12:13] neg_lo:[0,0,1] neg_hi:[0,0,1]
	v_pk_mul_f32 v[12:13], v[108:109], v[10:11]
	v_pk_mul_f32 v[0:1], v[0:1], v[194:195]
	v_pk_mul_f32 v[4:5], v[4:5], v[64:65] op_sel_hi:[1,0]
	v_pk_fma_f32 v[12:13], v[110:111], v[14:15], v[12:13]
	v_pk_mul_f32 v[14:15], v[108:109], v[14:15]
	v_pk_mul_f32 v[2:3], v[2:3], v[64:65] op_sel_hi:[1,0]
	v_pk_mul_f32 v[4:5], v[4:5], v[78:79]
	v_pk_fma_f32 v[10:11], v[110:111], v[10:11], v[14:15] neg_lo:[0,0,1] neg_hi:[0,0,1]
	v_pk_mul_f32 v[14:15], v[112:113], v[0:1]
	v_pk_mul_f32 v[2:3], v[2:3], v[192:193]
	v_pk_mul_f32 v[6:7], v[6:7], v[64:65] op_sel_hi:[1,0]
	v_pk_fma_f32 v[14:15], v[114:115], v[4:5], v[14:15]
	v_pk_mul_f32 v[4:5], v[112:113], v[4:5]
	v_pk_mul_f32 v[6:7], v[6:7], v[80:81]
	v_pk_fma_f32 v[0:1], v[114:115], v[0:1], v[4:5] neg_lo:[0,0,1] neg_hi:[0,0,1]
	v_pk_mul_f32 v[4:5], v[132:133], v[2:3]
	v_cvt_pk_bf16_f32 v108, v8, v9
	v_pk_mul_f32 v[8:9], v[64:65], v[52:53] op_sel_hi:[0,1]
	v_pk_fma_f32 v[4:5], v[134:135], v[6:7], v[4:5]
	v_cvt_pk_bf16_f32 v110, v0, v1
	v_cvt_pk_bf16_f32 v105, v12, v13
	v_pk_mul_f32 v[0:1], v[60:61], v[64:65] op_sel_hi:[1,0]
	v_pk_mul_f32 v[8:9], v[8:9], v[84:85]
	v_pk_mul_f32 v[12:13], v[64:65], v[54:55] op_sel_hi:[0,1]
	v_pk_mul_f32 v[6:7], v[132:133], v[6:7]
	v_cvt_pk_bf16_f32 v109, v10, v11
	v_cvt_pk_bf16_f32 v107, v4, v5
	v_pk_mul_f32 v[0:1], v[0:1], v[190:191]
	v_pk_mul_f32 v[4:5], v[62:63], v[64:65] op_sel_hi:[1,0]
	v_pk_mul_f32 v[10:11], v[64:65], v[48:49] op_sel_hi:[0,1]
	v_pk_mul_f32 v[12:13], v[12:13], v[82:83]
	v_pk_mul_f32 v[48:49], v[120:121], v[8:9]
	v_pk_mul_f32 v[8:9], v[122:123], v[8:9]
	v_pk_fma_f32 v[2:3], v[134:135], v[2:3], v[6:7] neg_lo:[0,0,1] neg_hi:[0,0,1]
	v_pk_mul_f32 v[4:5], v[4:5], v[188:189]
	v_pk_fma_f32 v[48:49], v[122:123], v[0:1], v[48:49] neg_lo:[0,0,1] neg_hi:[0,0,1]
	v_pk_fma_f32 v[8:9], v[120:121], v[0:1], v[8:9]
	v_pk_mul_f32 v[0:1], v[128:129], v[12:13]
	v_cvt_pk_bf16_f32 v111, v2, v3
	v_cvt_pk_bf16_f32 v106, v14, v15
	v_pk_mul_f32 v[2:3], v[64:65], v[56:57] op_sel_hi:[0,1]
	v_pk_mul_f32 v[10:11], v[10:11], v[86:87]
	v_pk_mul_f32 v[14:15], v[64:65], v[50:51] op_sel_hi:[0,1]
	v_pk_fma_f32 v[50:51], v[130:131], v[4:5], v[0:1] neg_lo:[0,0,1] neg_hi:[0,0,1]
	v_pk_mul_f32 v[0:1], v[130:131], v[12:13]
	v_pk_mul_f32 v[2:3], v[2:3], v[186:187]
	v_pk_fma_f32 v[52:53], v[128:129], v[4:5], v[0:1]
	v_pk_mul_f32 v[0:1], v[136:137], v[10:11]
	v_pk_mul_f32 v[6:7], v[64:65], v[58:59] op_sel_hi:[0,1]
	v_pk_mul_f32 v[14:15], v[14:15], v[88:89]
	v_pk_fma_f32 v[4:5], v[138:139], v[2:3], v[0:1] neg_lo:[0,0,1] neg_hi:[0,0,1]
	v_pk_mul_f32 v[0:1], v[138:139], v[10:11]
	v_pk_mul_f32 v[6:7], v[6:7], v[184:185]
	v_pk_fma_f32 v[54:55], v[136:137], v[2:3], v[0:1]
	v_pk_mul_f32 v[0:1], v[116:117], v[14:15]
	v_add_co_u32_e32 v2, vcc, s40, v180
	v_pk_fma_f32 v[10:11], v[118:119], v[6:7], v[0:1] neg_lo:[0,0,1] neg_hi:[0,0,1]
	s_waitcnt vmcnt(1)
	ds_write_b128 v204, v[66:69] offset:34816
	s_waitcnt vmcnt(0)
	ds_write_b128 v204, v[70:73] offset:44032
	v_lshl_add_u64 v[0:1], v[180:181], 0, s[14:15]
	v_addc_co_u32_e32 v3, vcc, 0, v181, vcc
	v_cvt_pk_bf16_f32 v99, v140, v141
	global_load_dwordx4 v[136:139], v[142:143], off offset:128
	v_pk_mul_f32 v[12:13], v[118:119], v[14:15]
	global_load_dwordx4 v[140:143], v[182:183], off offset:128
	global_load_dwordx4 v[128:131], v[2:3], off
	global_load_dwordx4 v[132:135], v[0:1], off offset:128
	s_waitcnt lgkmcnt(0)
	s_barrier
; DI unsigned cvtpk(float lo, float hi) { f32x2 v = {lo, hi}; return __builtin_bit_cast(unsigned, __builtin_convertvector(v, bf16x2_t)); }
; template <int NHQ, int NHKV>
; DI void attn_phase_l1(const u16* __restrict__ Q, const u16* __restrict__ K, const u16* __restrict__ Vt, u16* __restrict__ O, const float* __restrict__ qg, char* smem, const int wv) {
;     ...
;     {
;       const char* sk = kb0 + r32 * KSTR + hh * 16;
; #pragma unroll
;       for (int i = 0; i < 16; ++i) { s0[i] = 0.f; s1[i] = 0.f; }
; #pragma unroll
;       for (int i = 0; i < NS; ++i) {
;         const bf16x8 k0f = *(const bf16x8*)(sk + i * 32), k1f = *(const bf16x8*)(sk + 32 * KSTR + i * 32);
;         s0 = __builtin_amdgcn_mfma_f32_32x32x16_bf16(k0f, qf[i], s0, 0, 0, 0);
;         s1 = __builtin_amdgcn_mfma_f32_32x32x16_bf16(k1f, qf[i], s1, 0, 0, 0);
;       }
;       unsigned w_[16]; f32x2 ps2 = {0.f, 0.f};
; #pragma unroll
;       for (int i = 0; i < 8; ++i) { f32x2 v; v[0] = __builtin_amdgcn_exp2f(s0[2 * i]); v[1] = __builtin_amdgcn_exp2f(s0[2 * i + 1]); ps2 += v; w_[i] = cvtpk(v[0], v[1]); }
; #pragma unroll
;       for (int i = 0; i < 8; ++i) { f32x2 v; v[0] = __builtin_amdgcn_exp2f(s1[2 * i]); v[1] = __builtin_amdgcn_exp2f(s1[2 * i + 1]); ps2 += v; w_[8 + i] = cvtpk(v[0], v[1]); }
;       l += ps2[0] + ps2[1];
; #pragma unroll
;       for (int q = 0; q < 4; ++q) pb[q] = __builtin_bit_cast(bf16x8, u32x4{w_[4 * q], w_[4 * q + 1], w_[4 * q + 2], w_[4 * q + 3]});
;     }
	ds_read_b128 v[0:3], v205
	ds_read_b128 v[24:27], v205 offset:32
	v_pk_fma_f32 v[32:33], v[116:117], v[6:7], v[12:13]
	v_cvt_pk_bf16_f32 v118, v4, v5
	v_cvt_pk_bf16_f32 v119, v10, v11
	v_cvt_pk_bf16_f32 v112, v8, v9
	s_waitcnt lgkmcnt(1)
	v_mfma_f32_32x32x16_bf16 v[0:15], v[0:3], v[100:103], 0
	v_mul_f32_e64 v28, v64, v44
	v_mul_f32_e64 v29, v64, v45
	v_mul_f32_e64 v34, v28, v178
	v_mul_f32_e64 v35, v29, v179
	v_mul_f32_e64 v28, v64, v40
	v_mul_f32_e64 v29, v64, v41
	v_pk_mul_f32 v[36:37], v[28:29], v[174:175]
	ds_read_b128 v[28:31], v205 offset:64
	v_pk_mul_f32 v[16:17], v[64:65], v[16:17] op_sel_hi:[0,1]
	v_mul_f32_e32 v126, 0.15915494, v124
	s_waitcnt lgkmcnt(1)
	v_mfma_f32_32x32x16_bf16 v[0:15], v[24:27], v[108:111], v[0:15]
	v_mul_f32_e64 v24, v64, v46
	v_mul_f32_e64 v25, v64, v47
	v_mul_f32_e64 v38, v24, v176
	v_mul_f32_e64 v39, v25, v177
	v_mul_f32_e64 v24, v64, v42
	v_mul_f32_e64 v25, v64, v43
	v_pk_mul_f32 v[40:41], v[24:25], v[158:159]
	ds_read_b128 v[24:27], v205 offset:96
	v_mul_f32_e32 v127, 0.15915494, v125
	v_floor_f32_e32 v126, v126
	s_waitcnt lgkmcnt(1)
	v_mfma_f32_32x32x16_bf16 v[0:15], v[28:31], v[96:99], v[0:15]
	v_mul_f32_e64 v28, v16, v94
	v_mul_f32_e64 v29, v17, v95
	v_mul_f32_e64 v16, v64, v22
	v_mul_f32_e64 v17, v64, v23
	v_floor_f32_e32 v127, v127
	v_mul_f32_e32 v146, 0.15915494, v144
	v_mul_f32_e32 v147, 0.15915494, v145
	v_pk_mul_f32 v[30:31], v[16:17], v[90:91]
	v_pk_mul_f32 v[16:17], v[64:65], v[18:19] op_sel_hi:[0,1]
	v_fma_f32 v126, v124, 0.15915494, -v126
	v_fma_f32 v127, v125, 0.15915494, -v127
	v_floor_f32_e32 v146, v146
	v_floor_f32_e32 v147, v147
	v_mul_f32_e32 v150, 0.15915494, v148
	v_mul_f32_e32 v151, 0.15915494, v149
	v_cvt_pk_bf16_f32 v104, v74, v75
	v_pk_mul_f32 v[44:45], v[16:17], v[156:157]
	ds_read_b128 v[16:19], v205 offset:128
	v_sin_f32_e32 v124, v126
	v_sin_f32_e32 v125, v127
	v_fma_f32 v146, v144, 0.15915494, -v146
	v_fma_f32 v147, v145, 0.15915494, -v147
	v_floor_f32_e32 v150, v150
	v_floor_f32_e32 v151, v151
	s_waitcnt lgkmcnt(1)
	v_mfma_f32_32x32x16_bf16 v[0:15], v[24:27], v[104:107], v[0:15]
	v_cos_f32_e32 v126, v126
	v_cos_f32_e32 v127, v127
	v_sin_f32_e32 v144, v146
	v_sin_f32_e32 v145, v147
	v_fma_f32 v150, v148, 0.15915494, -v150
	v_fma_f32 v151, v149, 0.15915494, -v151
	v_cos_f32_e32 v146, v146
	v_cos_f32_e32 v147, v147
	v_sin_f32_e32 v148, v150
	v_sin_f32_e32 v149, v151
	v_pk_mul_f32 v[20:21], v[64:65], v[20:21] op_sel_hi:[0,1]
	v_cos_f32_e32 v150, v150
	v_cos_f32_e32 v151, v151
	v_pk_mul_f32 v[42:43], v[20:21], v[92:93]
	v_mul_f32_e32 v154, 0.15915494, v152
	v_pk_mul_f32 v[20:21], v[124:125], v[42:43]
	v_floor_f32_e32 v154, v154
	v_pk_fma_f32 v[24:25], v[126:127], v[34:35], v[20:21] neg_lo:[0,0,1] neg_hi:[0,0,1]
	v_pk_mul_f32 v[20:21], v[144:145], v[30:31]
	v_cvt_pk_bf16_f32 v116, v48, v49
	v_pk_fma_f32 v[26:27], v[146:147], v[38:39], v[20:21] neg_lo:[0,0,1] neg_hi:[0,0,1]
	v_pk_mul_f32 v[20:21], v[148:149], v[28:29]
	v_cvt_pk_bf16_f32 v117, v50, v51
	v_pk_fma_f32 v[46:47], v[150:151], v[36:37], v[20:21] neg_lo:[0,0,1] neg_hi:[0,0,1]
	ds_read_b128 v[20:23], v205 offset:160
	v_fma_f32 v154, v152, 0.15915494, -v154
	s_waitcnt lgkmcnt(1)
	v_mfma_f32_32x32x16_bf16 v[0:15], v[16:19], v[116:119], v[0:15]
	v_sin_f32_e32 v152, v154
	v_cos_f32_e32 v154, v154
	v_cvt_pk_bf16_f32 v120, v24, v25
	v_cvt_pk_bf16_f32 v121, v26, v27
	v_pk_mul_f32 v[16:17], v[152:153], v[44:45]
	v_cvt_pk_bf16_f32 v122, v46, v47
	v_pk_fma_f32 v[16:17], v[154:155], v[40:41], v[16:17] neg_lo:[0,0,1] neg_hi:[0,0,1]
	v_cvt_pk_bf16_f32 v113, v52, v53
	v_cvt_pk_bf16_f32 v123, v16, v17
	ds_read_b128 v[16:19], v205 offset:192
	v_cvt_pk_bf16_f32 v114, v54, v55
	s_waitcnt lgkmcnt(1)
	v_mfma_f32_32x32x16_bf16 v[0:15], v[20:23], v[120:123], v[0:15]
	v_mul_f32_e64 v20, v126, v42
	v_mul_f32_e64 v21, v127, v43
	v_cvt_pk_bf16_f32 v115, v32, v33
	v_fma_f32 v24, v124, v34, v20
	v_fma_f32 v25, v125, v35, v21
	v_pk_mul_f32 v[20:21], v[146:147], v[30:31]
	v_pk_mul_f32 v[28:29], v[150:151], v[28:29]
	v_pk_fma_f32 v[26:27], v[144:145], v[38:39], v[20:21]
	ds_read_b128 v[20:23], v205 offset:224
	s_waitcnt lgkmcnt(1)
	v_mfma_f32_32x32x16_bf16 v[0:15], v[16:19], v[112:115], v[0:15]
	v_mul_f32_e64 v18, v154, v44
	v_mul_f32_e64 v19, v155, v45
	v_fma_f32 v16, v148, v36, v28
	v_fma_f32 v17, v149, v37, v29
	v_fma_f32 v18, v152, v40, v18
	v_fma_f32 v19, v153, v41, v19
	v_cvt_pk_bf16_f32 v126, v16, v17
	v_cvt_pk_bf16_f32 v127, v18, v19
	ds_read_b128 v[16:19], v205 offset:8704
	ds_read_b128 v[32:35], v205 offset:8736
	v_cvt_pk_bf16_f32 v124, v24, v25
	v_cvt_pk_bf16_f32 v125, v26, v27
	v_mad_i64_i32 v[174:175], s[24:25], s42, v212, v[162:163]
	s_waitcnt lgkmcnt(2)
	v_mfma_f32_32x32x16_bf16 v[0:15], v[20:23], v[124:127], v[0:15]
	s_add_u32 s24, s20, s22
	s_addc_u32 s25, s21, s23
	s_mov_b32 s42, -1
	v_mov_b32_e32 v50, v165
	v_mov_b32_e32 v51, v165
	v_mov_b32_e32 v52, v165
	v_mov_b32_e32 v53, v165
	s_waitcnt lgkmcnt(1)
	v_mfma_f32_32x32x16_bf16 v[16:31], v[16:19], v[100:103], 0
	s_nop 2
	v_exp_f32_e32 v44, v0
	v_exp_f32_e32 v45, v1
	v_exp_f32_e32 v46, v2
	v_exp_f32_e32 v47, v3
	v_exp_f32_e32 v4, v4
	v_exp_f32_e32 v5, v5
	v_exp_f32_e32 v6, v6
	s_waitcnt lgkmcnt(0)
	v_mfma_f32_32x32x16_bf16 v[16:31], v[32:35], v[108:111], v[16:31]
	ds_read_b128 v[32:35], v205 offset:8768
	ds_read_b128 v[36:39], v205 offset:8800
	v_exp_f32_e32 v7, v7
	v_pk_add_f32 v[48:49], v[44:45], 0 op_sel_hi:[1,0]
	v_cvt_pk_bf16_f32 v80, v44, v45
	v_pk_add_f32 v[44:45], v[46:47], v[48:49]
	v_exp_f32_e32 v8, v8
	v_exp_f32_e32 v9, v9
	s_waitcnt lgkmcnt(1)
	v_mfma_f32_32x32x16_bf16 v[16:31], v[32:35], v[96:99], v[16:31]
	ds_read_b128 v[32:35], v205 offset:8832
	ds_read_b128 v[40:43], v205 offset:8864
	v_exp_f32_e32 v10, v10
	v_exp_f32_e32 v11, v11
	v_cvt_pk_bf16_f32 v146, v4, v5
	v_cvt_pk_bf16_f32 v147, v6, v7
	v_cvt_pk_bf16_f32 v145, v46, v47
	v_cvt_pk_bf16_f32 v84, v8, v9
	s_waitcnt lgkmcnt(2)
	v_mfma_f32_32x32x16_bf16 v[16:31], v[36:39], v[104:107], v[16:31]
	ds_read_b128 v[0:3], v205 offset:8896
	ds_read_b128 v[36:39], v205 offset:8928
	s_waitcnt lgkmcnt(0)
	s_barrier
; DI unsigned cvtpk(float lo, float hi) { f32x2 v = {lo, hi}; return __builtin_bit_cast(unsigned, __builtin_convertvector(v, bf16x2_t)); }
; #define B_LOADK(Kb_, tile_) do { const char* kp_ = (const char*)(Kb_) + (size_t)(tile_) * (64 * LDK * 2); const unsigned ko_ = ((tile_) == NT - 1) ? koffL : koff; \
;     _Pragma("unroll") for (int i_ = 0; i_ < NKC; ++i_) rk[i_] = *(const u32x4*)(kp_ + ko_ + i_ * 128); } while (0)
; #define B_LOADV(Vb_, tile_) do { const char* vp_ = (const char*)(Vb_) + (size_t)(tile_) * 128; \
;     rv[0] = *(const u32x4*)(vp_ + voff); rv[1] = *(const u32x4*)(vp_ + voff + 64 * LP * 2); } while (0)
; #define B_WRITEV(bi_) do { char* b_w = vb0 + (bi_) * VBYTES + vwoff; \
;     *(u32x4*)(b_w) = rv[0]; *(u32x4*)(b_w + 64 * VSTR) = rv[1]; } while (0)
; template <int NHQ, int NHKV>
; DI void attn_phase_l1(const u16* __restrict__ Q, const u16* __restrict__ K, const u16* __restrict__ Vt, u16* __restrict__ O, const float* __restrict__ qg, char* smem, const int wv) {
;     ...
; #pragma unroll
;     for (int d = 0; d < 4; ++d)
; #pragma unroll
;       for (int i = 0; i < 16; ++i) o[d][i] = 0.f;
;     __syncthreads();
;     B_LOADK(Kb, 0); B_WRITEK(0); B_LOADK(Kb, 1); B_WRITEK(1); B_LOADV(Vb, 0); B_WRITEV(0);
;     B_LOADK(Kb, 2); B_LOADV(Vb, 1);
;     __syncthreads();
;     {
;       const char* sk = kb0 + r32 * KSTR + hh * 16;
; #pragma unroll
;       for (int i = 0; i < 16; ++i) { s0[i] = 0.f; s1[i] = 0.f; }
; #pragma unroll
;       for (int i = 0; i < NS; ++i) {
;         const bf16x8 k0f = *(const bf16x8*)(sk + i * 32), k1f = *(const bf16x8*)(sk + 32 * KSTR + i * 32);
;         s0 = __builtin_amdgcn_mfma_f32_32x32x16_bf16(k0f, qf[i], s0, 0, 0, 0);
;         s1 = __builtin_amdgcn_mfma_f32_32x32x16_bf16(k1f, qf[i], s1, 0, 0, 0);
;       }
;       unsigned w_[16]; f32x2 ps2 = {0.f, 0.f};
; #pragma unroll
;       for (int i = 0; i < 8; ++i) { f32x2 v; v[0] = __builtin_amdgcn_exp2f(s0[2 * i]); v[1] = __builtin_amdgcn_exp2f(s0[2 * i + 1]); ps2 += v; w_[i] = cvtpk(v[0], v[1]); }
; #pragma unroll
;       for (int i = 0; i < 8; ++i) { f32x2 v; v[0] = __builtin_amdgcn_exp2f(s1[2 * i]); v[1] = __builtin_amdgcn_exp2f(s1[2 * i + 1]); ps2 += v; w_[8 + i] = cvtpk(v[0], v[1]); }
;       l += ps2[0] + ps2[1];
; #pragma unroll
;       for (int q = 0; q < 4; ++q) pb[q] = __builtin_bit_cast(bf16x8, u32x4{w_[4 * q], w_[4 * q + 1], w_[4 * q + 2], w_[4 * q + 3]});
;     }
	v_cvt_pk_bf16_f32 v149, v10, v11
	v_mov_b32_e32 v48, v165
	v_mov_b32_e32 v49, v165
	s_waitcnt lgkmcnt(3)
	v_mfma_f32_32x32x16_bf16 v[16:31], v[32:35], v[116:119], v[16:31]
	v_add_f32_e64 v32, v4, v44
	v_add_f32_e64 v33, v5, v45
	v_mov_b32_e32 v54, v165
	v_add_f32_e64 v4, v6, v32
	v_add_f32_e64 v5, v7, v33
	v_exp_f32_e32 v6, v12
	v_exp_f32_e32 v7, v13
	v_pk_add_f32 v[4:5], v[8:9], v[4:5]
	v_mov_b32_e32 v55, v165
	s_waitcnt lgkmcnt(2)
	v_mfma_f32_32x32x16_bf16 v[16:31], v[40:43], v[120:123], v[16:31]
	v_add_f32_e64 v4, v10, v4
	v_add_f32_e64 v5, v11, v5
	v_cvt_pk_bf16_f32 v150, v6, v7
	v_mov_b32_e32 v56, v165
	v_mov_b32_e32 v57, v165
	v_mov_b32_e32 v58, v165
	v_mov_b32_e32 v59, v165
	v_mov_b32_e32 v60, v165
	s_waitcnt lgkmcnt(1)
	v_mfma_f32_32x32x16_bf16 v[16:31], v[0:3], v[112:115], v[16:31]
	v_exp_f32_e32 v0, v14
	v_exp_f32_e32 v1, v15
	v_pk_add_f32 v[2:3], v[6:7], v[4:5]
	v_mov_b32_e32 v61, v165
	v_mov_b32_e32 v62, v165
	v_pk_add_f32 v[2:3], v[0:1], v[2:3]
	v_cvt_pk_bf16_f32 v151, v0, v1
	s_waitcnt lgkmcnt(0)
	v_mfma_f32_32x32x16_bf16 v[16:31], v[36:39], v[124:127], v[16:31]
	v_mov_b32_e32 v63, v165
	v_mov_b32_e32 v32, v165
	v_mov_b32_e32 v33, v165
	v_mov_b32_e32 v34, v165
	v_mov_b32_e32 v35, v165
	v_mov_b32_e32 v36, v165
	v_mov_b32_e32 v37, v165
	s_nop 4
	v_exp_f32_e32 v4, v16
	v_exp_f32_e32 v5, v17
	v_exp_f32_e32 v6, v18
	v_exp_f32_e32 v7, v19
	v_mov_b32_e32 v38, v165
	v_pk_add_f32 v[0:1], v[2:3], v[4:5]
	v_exp_f32_e32 v2, v20
	v_exp_f32_e32 v3, v21
	v_cvt_pk_bf16_f32 v88, v4, v5
	v_pk_add_f32 v[0:1], v[6:7], v[0:1]
	v_exp_f32_e32 v4, v22
	v_exp_f32_e32 v5, v23
	v_pk_add_f32 v[0:1], v[2:3], v[0:1]
	v_cvt_pk_bf16_f32 v154, v2, v3
	v_exp_f32_e32 v2, v24
	v_exp_f32_e32 v3, v25
	v_cvt_pk_bf16_f32 v153, v6, v7
	v_pk_add_f32 v[0:1], v[4:5], v[0:1]
	v_exp_f32_e32 v6, v26
	v_exp_f32_e32 v7, v27
	v_pk_add_f32 v[0:1], v[2:3], v[0:1]
	v_cvt_pk_bf16_f32 v92, v2, v3
	v_exp_f32_e32 v2, v28
	v_exp_f32_e32 v3, v29
	v_cvt_pk_bf16_f32 v155, v4, v5
	v_exp_f32_e32 v4, v30
	v_exp_f32_e32 v5, v31
	v_pk_add_f32 v[0:1], v[6:7], v[0:1]
	v_cvt_pk_bf16_f32 v157, v6, v7
	v_pk_add_f32 v[0:1], v[2:3], v[0:1]
	v_cvt_pk_bf16_f32 v158, v2, v3
	v_pk_add_f32 v[0:1], v[4:5], v[0:1]
	v_cvt_pk_bf16_f32 v159, v4, v5
	v_add_f32_e32 v0, v0, v1
	v_add_f32_e32 v176, 0, v0
	v_mov_b32_e32 v39, v165
	v_mov_b32_e32 v40, v165
	v_mov_b32_e32 v41, v165
	v_mov_b32_e32 v42, v165
	v_mov_b32_e32 v43, v165
	v_mov_b32_e32 v44, v165
	v_mov_b32_e32 v45, v165
	v_mov_b32_e32 v46, v165
	v_mov_b32_e32 v47, v165
	v_mov_b32_e32 v16, v165
	v_mov_b32_e32 v17, v165
	v_mov_b32_e32 v18, v165
	v_mov_b32_e32 v19, v165
	v_mov_b32_e32 v20, v165
	v_mov_b32_e32 v21, v165
	v_mov_b32_e32 v22, v165
	v_mov_b32_e32 v23, v165
	v_mov_b32_e32 v24, v165
	v_mov_b32_e32 v25, v165
	v_mov_b32_e32 v26, v165
	v_mov_b32_e32 v27, v165
	v_mov_b32_e32 v28, v165
	v_mov_b32_e32 v29, v165
	v_mov_b32_e32 v30, v165
	v_mov_b32_e32 v31, v165
	v_mov_b32_e32 v0, v165
	v_mov_b32_e32 v1, v165
	v_mov_b32_e32 v2, v165
	v_mov_b32_e32 v3, v165
	v_mov_b32_e32 v4, v165
	v_mov_b32_e32 v5, v165
	v_mov_b32_e32 v6, v165
	v_mov_b32_e32 v7, v165
	v_mov_b32_e32 v8, v165
	v_mov_b32_e32 v9, v165
	v_mov_b32_e32 v10, v165
	v_mov_b32_e32 v11, v165
	v_mov_b32_e32 v12, v165
	v_mov_b32_e32 v13, v165
	v_mov_b32_e32 v14, v165
	v_mov_b32_e32 v15, v165
	s_cmp_ge_u32 s3, 4
	s_cbranch_scc1 .Lb_first
	.p2align 3

; template <int NHQ, int NHKV>
; DI void attn_phase_l1(const u16* __restrict__ Q, const u16* __restrict__ K, const u16* __restrict__ Vt, u16* __restrict__ O, const float* __restrict__ qg, char* smem, const int wv) {
;     ...
;       for (int q = 0; q < 4; ++q) pb[q] = __builtin_bit_cast(bf16x8, u32x4{w_[4 * q], w_[4 * q + 1], w_[4 * q + 2], w_[4 * q + 3]});
;     }
;     asm volatile("s_waitcnt lgkmcnt(0)" ::: "memory"); __builtin_amdgcn_s_barrier(); asm volatile("" ::: "memory");
;     for (int j = 0; j < NT; ++j) {
.Lb_first:
	v_mov_b32_e32 v156, v92
	v_mov_b32_e32 v152, v88
	v_mov_b32_e32 v148, v84
	v_mov_b32_e32 v144, v80
	s_branch .Lb_body
	.p2align 3

; template <class Epi>
; DI void gemm_phase(PG8_LAS unsigned char* lds, const Gemm g, const StaticOrder& S, const Epi& E, const int wv) {
;     ...
;     const bool has_next = S.next(ui + 1, nxt);
;     const char* nA = has_next ? (const char*)g.A + (size_t)nxt.pm * tstep : cA; const char* nB = has_next ? (const char*)g.Bt + (size_t)nxt.pn * tstep : cB;
;     ...
; #pragma unroll
;     for (int a = 0; a < 2; ++a)
; #pragma unroll
;       for (int b = 0; b < 2; ++b)
; #pragma unroll
;         for (int m = 0; m < 4; ++m)
; #pragma unroll
;           for (int n = 0; n < 2; ++n) acc[a][b][m][n] = (f32x4){0.f, 0.f, 0.f, 0.f};
;     cur = nxt; cA = nA; cB = nB; ++ui;
.LBB0_1283:
	s_ashr_i32 s25, s24, 31
	s_lshl_b64 s[26:27], s[24:25], 19
	s_add_u32 s26, s6, s26
	s_addc_u32 s27, s7, s27
	s_and_b64 s[28:29], exec, s[20:21]
	s_cselect_b32 s25, s37, s27
	s_cselect_b32 s31, s36, s26
	s_ashr_i32 s23, s22, 31
	s_lshl_b64 s[28:29], s[22:23], 19
	s_add_u32 s28, s44, s28
	s_addc_u32 s29, s45, s29
	s_and_b64 s[40:41], exec, s[20:21]
	s_cselect_b32 s23, s39, s29
	s_cselect_b32 s35, s38, s28
	s_add_u32 s36, s36, 0x40080
	s_addc_u32 s37, s37, 0
	s_add_u32 s62, s38, 0x100
	v_mov_b32_e32 v0, 0
	s_addc_u32 s63, s39, 0
	s_mov_b32 s64, -2
	s_waitcnt lgkmcnt(0)
	v_mov_b32_e32 v1, v0
	v_mov_b32_e32 v2, v0
	v_mov_b32_e32 v3, v0
	v_mov_b32_e32 v4, v0
	v_mov_b32_e32 v5, v0
	v_mov_b32_e32 v6, v0
	v_mov_b32_e32 v7, v0
	v_mov_b32_e32 v16, v0
	v_mov_b32_e32 v17, v0
	v_mov_b32_e32 v18, v0
	v_mov_b32_e32 v19, v0
	v_mov_b32_e32 v20, v0
	v_mov_b32_e32 v21, v0
	v_mov_b32_e32 v22, v0
	v_mov_b32_e32 v23, v0
	v_mov_b32_e32 v32, v0
	v_mov_b32_e32 v33, v0
	v_mov_b32_e32 v34, v0
	v_mov_b32_e32 v35, v0
	v_mov_b32_e32 v36, v0
	v_mov_b32_e32 v37, v0
	v_mov_b32_e32 v38, v0
	v_mov_b32_e32 v39, v0
	v_mov_b32_e32 v48, v0
	v_mov_b32_e32 v49, v0
	v_mov_b32_e32 v50, v0
	v_mov_b32_e32 v51, v0
	v_mov_b32_e32 v52, v0
	v_mov_b32_e32 v53, v0
	v_mov_b32_e32 v54, v0
	v_mov_b32_e32 v55, v0
	v_mov_b32_e32 v8, v0
	v_mov_b32_e32 v9, v0
	v_mov_b32_e32 v10, v0
	v_mov_b32_e32 v11, v0
	v_mov_b32_e32 v12, v0
	v_mov_b32_e32 v13, v0
	v_mov_b32_e32 v14, v0
	v_mov_b32_e32 v15, v0
	v_mov_b32_e32 v24, v0
	v_mov_b32_e32 v25, v0
	v_mov_b32_e32 v26, v0
	v_mov_b32_e32 v27, v0
	v_mov_b32_e32 v28, v0
	v_mov_b32_e32 v29, v0
	v_mov_b32_e32 v30, v0
	v_mov_b32_e32 v31, v0
	v_mov_b32_e32 v40, v0
	v_mov_b32_e32 v41, v0
	v_mov_b32_e32 v42, v0
	v_mov_b32_e32 v43, v0
	v_mov_b32_e32 v44, v0
	v_mov_b32_e32 v45, v0
	v_mov_b32_e32 v46, v0
	v_mov_b32_e32 v47, v0
	v_mov_b32_e32 v56, v0
	v_mov_b32_e32 v57, v0
	v_mov_b32_e32 v58, v0
	v_mov_b32_e32 v59, v0
	v_mov_b32_e32 v60, v0
	v_mov_b32_e32 v61, v0
	v_mov_b32_e32 v62, v0
	v_mov_b32_e32 v63, v0
	v_mov_b32_e32 v64, v0
	v_mov_b32_e32 v65, v0
	v_mov_b32_e32 v66, v0
	v_mov_b32_e32 v67, v0
	v_mov_b32_e32 v68, v0
	v_mov_b32_e32 v69, v0
	v_mov_b32_e32 v70, v0
	v_mov_b32_e32 v71, v0
	v_mov_b32_e32 v80, v0
	v_mov_b32_e32 v81, v0
	v_mov_b32_e32 v82, v0
	v_mov_b32_e32 v83, v0
	v_mov_b32_e32 v84, v0
	v_mov_b32_e32 v85, v0
	v_mov_b32_e32 v86, v0
	v_mov_b32_e32 v87, v0
	v_mov_b32_e32 v96, v0
	v_mov_b32_e32 v97, v0
	v_mov_b32_e32 v98, v0
	v_mov_b32_e32 v99, v0
	v_mov_b32_e32 v100, v0
	v_mov_b32_e32 v101, v0
	v_mov_b32_e32 v102, v0
	v_mov_b32_e32 v103, v0
	v_mov_b32_e32 v112, v0
	v_mov_b32_e32 v113, v0
	v_mov_b32_e32 v114, v0
	v_mov_b32_e32 v115, v0
	v_mov_b32_e32 v116, v0
	v_mov_b32_e32 v117, v0
	v_mov_b32_e32 v118, v0
	v_mov_b32_e32 v119, v0
	v_mov_b32_e32 v72, v0
	v_mov_b32_e32 v73, v0
	v_mov_b32_e32 v74, v0
	v_mov_b32_e32 v75, v0
	v_mov_b32_e32 v76, v0
	v_mov_b32_e32 v77, v0
	v_mov_b32_e32 v78, v0
	v_mov_b32_e32 v79, v0
	v_mov_b32_e32 v88, v0
	v_mov_b32_e32 v89, v0
	v_mov_b32_e32 v90, v0
	v_mov_b32_e32 v91, v0
	v_mov_b32_e32 v92, v0
	v_mov_b32_e32 v93, v0
	v_mov_b32_e32 v94, v0
	v_mov_b32_e32 v95, v0
	v_mov_b32_e32 v104, v0
	v_mov_b32_e32 v105, v0
	v_mov_b32_e32 v106, v0
	v_mov_b32_e32 v107, v0
	v_mov_b32_e32 v108, v0
	v_mov_b32_e32 v109, v0
	v_mov_b32_e32 v110, v0
	v_mov_b32_e32 v111, v0
	v_mov_b32_e32 v120, v0
	v_mov_b32_e32 v121, v0
	v_mov_b32_e32 v122, v0
	v_mov_b32_e32 v123, v0
	v_mov_b32_e32 v124, v0
	v_mov_b32_e32 v125, v0
	v_mov_b32_e32 v126, v0
	v_mov_b32_e32 v127, v0
	.p2align 3

; template <class Epi>
; DI void gemm_phase(PG8_LAS unsigned char* lds, const Gemm g, const StaticOrder& S, const Epi& E, const int wv) {
;     ...
;     const bool has_next = S.next(ui + 1, nxt);
;     const char* nA = has_next ? (const char*)g.A + (size_t)nxt.pm * tstep : cA; const char* nB = has_next ? (const char*)g.Bt + (size_t)nxt.pn * tstep : cB;
;     ...
; #pragma unroll
;     for (int a = 0; a < 2; ++a)
; #pragma unroll
;       for (int b = 0; b < 2; ++b)
; #pragma unroll
;         for (int m = 0; m < 4; ++m)
; #pragma unroll
;           for (int n = 0; n < 2; ++n) acc[a][b][m][n] = (f32x4){0.f, 0.f, 0.f, 0.f};
;     cur = nxt; cA = nA; cB = nB; ++ui;
.LBB0_1366:
	s_ashr_i32 s25, s24, 31
	s_lshl_b64 s[26:27], s[24:25], 19
	s_add_u32 s26, s38, s26
	s_addc_u32 s27, s39, s27
	s_and_b64 s[28:29], exec, s[20:21]
	s_cselect_b32 s5, s7, s27
	s_cselect_b32 s25, s6, s26
	s_ashr_i32 s23, s22, 31
	s_lshl_b64 s[28:29], s[22:23], 19
	s_add_u32 s28, s40, s28
	s_addc_u32 s29, s41, s29
	s_and_b64 s[34:35], exec, s[20:21]
	s_cselect_b32 s23, s9, s29
	s_cselect_b32 s58, s8, s28
	s_add_u32 s6, s6, 0x40080
	s_addc_u32 s7, s7, 0
	s_add_u32 s59, s8, 0x100
	v_mov_b32_e32 v0, 0
	s_addc_u32 s60, s9, 0
	s_mov_b32 s61, -2
	v_mov_b32_e32 v1, v0
	v_mov_b32_e32 v2, v0
	v_mov_b32_e32 v3, v0
	v_mov_b32_e32 v8, v0
	v_mov_b32_e32 v9, v0
	v_mov_b32_e32 v10, v0
	v_mov_b32_e32 v11, v0
	v_mov_b32_e32 v16, v0
	v_mov_b32_e32 v17, v0
	v_mov_b32_e32 v18, v0
	v_mov_b32_e32 v19, v0
	v_mov_b32_e32 v24, v0
	v_mov_b32_e32 v25, v0
	v_mov_b32_e32 v26, v0
	v_mov_b32_e32 v27, v0
	v_mov_b32_e32 v32, v0
	v_mov_b32_e32 v33, v0
	v_mov_b32_e32 v34, v0
	v_mov_b32_e32 v35, v0
	v_mov_b32_e32 v40, v0
	v_mov_b32_e32 v41, v0
	v_mov_b32_e32 v42, v0
	v_mov_b32_e32 v43, v0
	v_mov_b32_e32 v56, v0
	v_mov_b32_e32 v57, v0
	v_mov_b32_e32 v58, v0
	v_mov_b32_e32 v59, v0
	v_mov_b32_e32 v60, v0
	v_mov_b32_e32 v61, v0
	v_mov_b32_e32 v62, v0
	v_mov_b32_e32 v63, v0
	v_mov_b32_e32 v4, v0
	v_mov_b32_e32 v5, v0
	v_mov_b32_e32 v6, v0
	v_mov_b32_e32 v7, v0
	v_mov_b32_e32 v12, v0
	v_mov_b32_e32 v13, v0
	v_mov_b32_e32 v14, v0
	v_mov_b32_e32 v15, v0
	v_mov_b32_e32 v20, v0
	v_mov_b32_e32 v21, v0
	v_mov_b32_e32 v22, v0
	v_mov_b32_e32 v23, v0
	v_mov_b32_e32 v28, v0
	v_mov_b32_e32 v29, v0
	v_mov_b32_e32 v30, v0
	v_mov_b32_e32 v31, v0
	v_mov_b32_e32 v36, v0
	v_mov_b32_e32 v37, v0
	v_mov_b32_e32 v38, v0
	v_mov_b32_e32 v39, v0
	v_mov_b32_e32 v44, v0
	v_mov_b32_e32 v45, v0
	v_mov_b32_e32 v46, v0
	v_mov_b32_e32 v47, v0
	v_mov_b32_e32 v48, v0
	v_mov_b32_e32 v49, v0
	v_mov_b32_e32 v50, v0
	v_mov_b32_e32 v51, v0
	v_mov_b32_e32 v52, v0
	v_mov_b32_e32 v53, v0
	v_mov_b32_e32 v54, v0
	v_mov_b32_e32 v55, v0
	v_mov_b32_e32 v64, v0
	v_mov_b32_e32 v65, v0
	v_mov_b32_e32 v66, v0
	v_mov_b32_e32 v67, v0
	v_mov_b32_e32 v72, v0
	v_mov_b32_e32 v73, v0
	v_mov_b32_e32 v74, v0
	v_mov_b32_e32 v75, v0
	v_mov_b32_e32 v80, v0
	v_mov_b32_e32 v81, v0
	v_mov_b32_e32 v82, v0
	v_mov_b32_e32 v83, v0
	v_mov_b32_e32 v88, v0
	v_mov_b32_e32 v89, v0
	v_mov_b32_e32 v90, v0
	v_mov_b32_e32 v91, v0
	v_mov_b32_e32 v96, v0
	v_mov_b32_e32 v97, v0
	v_mov_b32_e32 v98, v0
	v_mov_b32_e32 v99, v0
	v_mov_b32_e32 v104, v0
	v_mov_b32_e32 v105, v0
	v_mov_b32_e32 v106, v0
	v_mov_b32_e32 v107, v0
	v_mov_b32_e32 v120, v0
	v_mov_b32_e32 v121, v0
	v_mov_b32_e32 v122, v0
	v_mov_b32_e32 v123, v0
	v_mov_b32_e32 v124, v0
	v_mov_b32_e32 v125, v0
	v_mov_b32_e32 v126, v0
	v_mov_b32_e32 v127, v0
	v_mov_b32_e32 v68, v0
	v_mov_b32_e32 v69, v0
	v_mov_b32_e32 v70, v0
	v_mov_b32_e32 v71, v0
	v_mov_b32_e32 v76, v0
	v_mov_b32_e32 v77, v0
	v_mov_b32_e32 v78, v0
	v_mov_b32_e32 v79, v0
	v_mov_b32_e32 v84, v0
	v_mov_b32_e32 v85, v0
	v_mov_b32_e32 v86, v0
	v_mov_b32_e32 v87, v0
	v_mov_b32_e32 v92, v0
	v_mov_b32_e32 v93, v0
	v_mov_b32_e32 v94, v0
	v_mov_b32_e32 v95, v0
	v_mov_b32_e32 v100, v0
	v_mov_b32_e32 v101, v0
	v_mov_b32_e32 v102, v0
	v_mov_b32_e32 v103, v0
	v_mov_b32_e32 v108, v0
	v_mov_b32_e32 v109, v0
	v_mov_b32_e32 v110, v0
	v_mov_b32_e32 v111, v0
	v_mov_b32_e32 v112, v0
	v_mov_b32_e32 v113, v0
	v_mov_b32_e32 v114, v0
	v_mov_b32_e32 v115, v0
	v_mov_b32_e32 v116, v0
	v_mov_b32_e32 v117, v0
	v_mov_b32_e32 v118, v0
	v_mov_b32_e32 v119, v0
	.p2align 3

; template <class Epi>
; DI void gemm_phase(PG8_LAS unsigned char* lds, const Gemm g, const StaticOrder& S, const Epi& E, const int wv) {
;     ...
; #pragma unroll
;     for (int a = 0; a < 2; ++a)
; #pragma unroll
;       for (int b = 0; b < 2; ++b)
; #pragma unroll
;         for (int m = 0; m < 4; ++m)
; #pragma unroll
;           for (int n = 0; n < 2; ++n) acc[a][b][m][n] = (f32x4){0.f, 0.f, 0.f, 0.f};
;     cur = nxt; cA = nA; cB = nB; ++ui;
.LBB0_1438:
	s_add_u32 s45, s16, 0x100
	v_mov_b32_e32 v0, 0
	s_addc_u32 s46, s17, 0
	s_mov_b32 s47, -2
	v_mov_b32_e32 v1, v0
	v_mov_b32_e32 v2, v0
	v_mov_b32_e32 v3, v0
	v_mov_b32_e32 v4, v0
	v_mov_b32_e32 v5, v0
	v_mov_b32_e32 v6, v0
	v_mov_b32_e32 v7, v0
	v_mov_b32_e32 v12, v0
	v_mov_b32_e32 v13, v0
	v_mov_b32_e32 v14, v0
	v_mov_b32_e32 v15, v0
	v_mov_b32_e32 v20, v0
	v_mov_b32_e32 v21, v0
	v_mov_b32_e32 v22, v0
	v_mov_b32_e32 v23, v0
	v_mov_b32_e32 v28, v0
	v_mov_b32_e32 v29, v0
	v_mov_b32_e32 v30, v0
	v_mov_b32_e32 v31, v0
	v_mov_b32_e32 v36, v0
	v_mov_b32_e32 v37, v0
	v_mov_b32_e32 v38, v0
	v_mov_b32_e32 v39, v0
	v_mov_b32_e32 v44, v0
	v_mov_b32_e32 v45, v0
	v_mov_b32_e32 v46, v0
	v_mov_b32_e32 v47, v0
	v_mov_b32_e32 v52, v0
	v_mov_b32_e32 v53, v0
	v_mov_b32_e32 v54, v0
	v_mov_b32_e32 v55, v0
	v_mov_b32_e32 v8, v0
	v_mov_b32_e32 v9, v0
	v_mov_b32_e32 v10, v0
	v_mov_b32_e32 v11, v0
	v_mov_b32_e32 v16, v0
	v_mov_b32_e32 v17, v0
	v_mov_b32_e32 v18, v0
	v_mov_b32_e32 v19, v0
	v_mov_b32_e32 v24, v0
	v_mov_b32_e32 v25, v0
	v_mov_b32_e32 v26, v0
	v_mov_b32_e32 v27, v0
	v_mov_b32_e32 v32, v0
	v_mov_b32_e32 v33, v0
	v_mov_b32_e32 v34, v0
	v_mov_b32_e32 v35, v0
	v_mov_b32_e32 v40, v0
	v_mov_b32_e32 v41, v0
	v_mov_b32_e32 v42, v0
	v_mov_b32_e32 v43, v0
	v_mov_b32_e32 v48, v0
	v_mov_b32_e32 v49, v0
	v_mov_b32_e32 v50, v0
	v_mov_b32_e32 v51, v0
	v_mov_b32_e32 v56, v0
	v_mov_b32_e32 v57, v0
	v_mov_b32_e32 v58, v0
	v_mov_b32_e32 v59, v0
	v_mov_b32_e32 v60, v0
	v_mov_b32_e32 v61, v0
	v_mov_b32_e32 v62, v0
	v_mov_b32_e32 v63, v0
	v_mov_b32_e32 v64, v0
	v_mov_b32_e32 v65, v0
	v_mov_b32_e32 v66, v0
	v_mov_b32_e32 v67, v0
	v_mov_b32_e32 v68, v0
	v_mov_b32_e32 v69, v0
	v_mov_b32_e32 v70, v0
	v_mov_b32_e32 v71, v0
	v_mov_b32_e32 v76, v0
	v_mov_b32_e32 v77, v0
	v_mov_b32_e32 v78, v0
	v_mov_b32_e32 v79, v0
	v_mov_b32_e32 v84, v0
	v_mov_b32_e32 v85, v0
	v_mov_b32_e32 v86, v0
	v_mov_b32_e32 v87, v0
	v_mov_b32_e32 v92, v0
	v_mov_b32_e32 v93, v0
	v_mov_b32_e32 v94, v0
	v_mov_b32_e32 v95, v0
	v_mov_b32_e32 v100, v0
	v_mov_b32_e32 v101, v0
	v_mov_b32_e32 v102, v0
	v_mov_b32_e32 v103, v0
	v_mov_b32_e32 v108, v0
	v_mov_b32_e32 v109, v0
	v_mov_b32_e32 v110, v0
	v_mov_b32_e32 v111, v0
	v_mov_b32_e32 v116, v0
	v_mov_b32_e32 v117, v0
	v_mov_b32_e32 v118, v0
	v_mov_b32_e32 v119, v0
	v_mov_b32_e32 v72, v0
	v_mov_b32_e32 v73, v0
	v_mov_b32_e32 v74, v0
	v_mov_b32_e32 v75, v0
	v_mov_b32_e32 v80, v0
	v_mov_b32_e32 v81, v0
	v_mov_b32_e32 v82, v0
	v_mov_b32_e32 v83, v0
	v_mov_b32_e32 v88, v0
	v_mov_b32_e32 v89, v0
	v_mov_b32_e32 v90, v0
	v_mov_b32_e32 v91, v0
	v_mov_b32_e32 v96, v0
	v_mov_b32_e32 v97, v0
	v_mov_b32_e32 v98, v0
	v_mov_b32_e32 v99, v0
	v_mov_b32_e32 v104, v0
	v_mov_b32_e32 v105, v0
	v_mov_b32_e32 v106, v0
	v_mov_b32_e32 v107, v0
	v_mov_b32_e32 v112, v0
	v_mov_b32_e32 v113, v0
	v_mov_b32_e32 v114, v0
	v_mov_b32_e32 v115, v0
	v_mov_b32_e32 v120, v0
	v_mov_b32_e32 v121, v0
	v_mov_b32_e32 v122, v0
	v_mov_b32_e32 v123, v0
	v_mov_b32_e32 v124, v0
	v_mov_b32_e32 v125, v0
	v_mov_b32_e32 v126, v0
	v_mov_b32_e32 v127, v0
	.p2align 3
